# v60 + first K-iteration of each GEMM main loop peeled: first MFMA per accumulator takes srcC=0, 128-VGPR zeroing block removed
# speedup vs baseline: 1.0360x; 1.0165x over previous
.LBB0_179:
	s_ashr_i32 s45, s44, 31
	s_lshl_b64 s[28:29], s[44:45], 19
	s_add_u32 s46, s96, s28
	s_addc_u32 s47, s97, s29
	s_and_b64 s[28:29], s[36:37], exec
	s_cselect_b32 s45, s47, s51
	s_cselect_b32 s67, s46, s50
	s_ashr_i32 s43, s42, 31
	s_lshl_b64 s[28:29], s[42:43], 19
	s_add_u32 s48, s2, s28
	s_addc_u32 s49, s56, s29
	s_and_b64 s[28:29], s[36:37], exec
	s_cselect_b32 s43, s49, s53
	s_cselect_b32 s68, s48, s52
	s_add_u32 s50, s50, 0x40080
	s_addc_u32 s51, s51, 0
	s_add_u32 s69, s52, 0x100
	s_addc_u32 s70, s53, 0
	s_mov_b32 s71, -2
	s_waitcnt lgkmcnt(0)
	s_add_u32 s28, s50, 0xfffc0080
	s_addc_u32 s29, s51, -1
	s_add_i32 s72, 0, 0x10000
	s_cmp_eq_u32 s71, 12
	s_cselect_b32 s55, s45, s29
	s_cselect_b32 s54, s67, s28
	s_cselect_b32 s53, s43, s70
	s_cselect_b32 s52, s68, s69
	s_add_i32 s73, 0, 0x14000
	ds_read_b128 v[158:161], v254
	ds_read_b128 v[162:165], v254 offset:1024
	ds_read_b128 v[166:169], v254 offset:2048
	ds_read_b128 v[170:173], v254 offset:3072
	ds_read_b128 v[174:177], v254 offset:16384
	ds_read_b128 v[178:181], v254 offset:17408
	ds_read_b128 v[182:185], v254 offset:18432
	ds_read_b128 v[186:189], v254 offset:19456
	s_add_i32 m0, s58, 0xc000
	ds_read_b128 v[190:193], v157
	ds_read_b128 v[194:197], v157 offset:1024
	ds_read_b128 v[198:201], v157 offset:2048
	ds_read_b128 v[202:205], v157 offset:3072
	ds_read_b128 v[206:209], v157 offset:4096
	ds_read_b128 v[210:213], v157 offset:5120
	ds_read_b128 v[214:217], v157 offset:6144
	ds_read_b128 v[218:221], v157 offset:7168
	global_load_lds_dwordx4 v134, s[50:51]
	s_add_i32 m0, s58, 0xe000
	s_nop 0
	global_load_lds_dwordx4 v136, s[50:51]
	s_waitcnt vmcnt(8)
	s_waitcnt lgkmcnt(0)
	s_barrier
	s_setprio 1
	s_waitcnt lgkmcnt(0)
	v_mfma_f32_16x16x32_bf16 v[124:127], v[158:161], v[190:193], 0
	v_mfma_f32_16x16x32_bf16 v[116:119], v[166:169], v[190:193], 0
	v_mfma_f32_16x16x32_bf16 v[108:111], v[158:161], v[198:201], 0
	v_mfma_f32_16x16x32_bf16 v[100:103], v[166:169], v[198:201], 0
	v_mfma_f32_16x16x32_bf16 v[92:95], v[158:161], v[206:209], 0
	v_mfma_f32_16x16x32_bf16 v[84:87], v[166:169], v[206:209], 0
	v_mfma_f32_16x16x32_bf16 v[76:79], v[158:161], v[214:217], 0
	v_mfma_f32_16x16x32_bf16 v[68:71], v[166:169], v[214:217], 0
	v_mfma_f32_16x16x32_bf16 v[124:127], v[162:165], v[194:197], v[124:127]
	v_mfma_f32_16x16x32_bf16 v[116:119], v[170:173], v[194:197], v[116:119]
	v_mfma_f32_16x16x32_bf16 v[108:111], v[162:165], v[202:205], v[108:111]
	v_mfma_f32_16x16x32_bf16 v[100:103], v[170:173], v[202:205], v[100:103]
	v_mfma_f32_16x16x32_bf16 v[92:95], v[162:165], v[210:213], v[92:95]
	v_mfma_f32_16x16x32_bf16 v[84:87], v[170:173], v[210:213], v[84:87]
	v_mfma_f32_16x16x32_bf16 v[76:79], v[162:165], v[218:221], v[76:79]
	v_mfma_f32_16x16x32_bf16 v[68:71], v[170:173], v[218:221], v[68:71]
	v_mfma_f32_16x16x32_bf16 v[120:123], v[174:177], v[190:193], 0
	v_mfma_f32_16x16x32_bf16 v[112:115], v[182:185], v[190:193], 0
	v_mfma_f32_16x16x32_bf16 v[104:107], v[174:177], v[198:201], 0
	v_mfma_f32_16x16x32_bf16 v[96:99], v[182:185], v[198:201], 0
	v_mfma_f32_16x16x32_bf16 v[88:91], v[174:177], v[206:209], 0
	v_mfma_f32_16x16x32_bf16 v[80:83], v[182:185], v[206:209], 0
	v_mfma_f32_16x16x32_bf16 v[72:75], v[174:177], v[214:217], 0
	v_mfma_f32_16x16x32_bf16 v[64:67], v[182:185], v[214:217], 0
	v_mfma_f32_16x16x32_bf16 v[120:123], v[178:181], v[194:197], v[120:123]
	v_mfma_f32_16x16x32_bf16 v[112:115], v[186:189], v[194:197], v[112:115]
	v_mfma_f32_16x16x32_bf16 v[104:107], v[178:181], v[202:205], v[104:107]
	v_mfma_f32_16x16x32_bf16 v[96:99], v[186:189], v[202:205], v[96:99]
	v_mfma_f32_16x16x32_bf16 v[88:91], v[178:181], v[210:213], v[88:91]
	v_mfma_f32_16x16x32_bf16 v[80:83], v[186:189], v[210:213], v[80:83]
	v_mfma_f32_16x16x32_bf16 v[72:75], v[178:181], v[218:221], v[72:75]
	v_mfma_f32_16x16x32_bf16 v[64:67], v[186:189], v[218:221], v[64:67]
	s_setprio 0
	s_barrier
	s_add_i32 s28, s72, s57
	s_mov_b32 m0, s28
	ds_read_b128 v[190:193], v157 offset:16384
	ds_read_b128 v[194:197], v157 offset:17408
	ds_read_b128 v[198:201], v157 offset:18432
	ds_read_b128 v[202:205], v157 offset:19456
	ds_read_b128 v[206:209], v157 offset:20480
	ds_read_b128 v[210:213], v157 offset:21504
	ds_read_b128 v[214:217], v157 offset:22528
	ds_read_b128 v[218:221], v157 offset:23552
	global_load_lds_dwordx4 v142, s[52:53]
	s_add_u32 s98, s52, 0x80
	s_addc_u32 s99, s53, 0
	s_add_i32 m0, s28, 0x2000
	s_add_u32 s28, s52, 0x40000
	s_addc_u32 s29, s53, 0
	s_add_i32 s72, s73, s57
	global_load_lds_dwordx4 v128, s[52:53]
	s_mov_b32 m0, s72
	s_nop 0
	global_load_lds_dwordx4 v142, s[28:29]
	s_add_i32 m0, s72, 0x2000
	s_nop 0
	global_load_lds_dwordx4 v128, s[28:29]
	s_mov_b32 m0, s58
	s_nop 0
	global_load_lds_dwordx4 v132, s[54:55]
	s_add_u32 s100, s54, 0x80
	s_addc_u32 s101, s55, 0
	s_mov_b32 m0, s59
	s_nop 0
	global_load_lds_dwordx4 v130, s[54:55]
	s_waitcnt vmcnt(8)
	s_waitcnt lgkmcnt(0)
	s_barrier
	s_setprio 1
	s_waitcnt lgkmcnt(0)
	v_mfma_f32_16x16x32_bf16 v[60:63], v[158:161], v[190:193], 0
	v_mfma_f32_16x16x32_bf16 v[52:55], v[166:169], v[190:193], 0
	v_mfma_f32_16x16x32_bf16 v[44:47], v[158:161], v[198:201], 0
	v_mfma_f32_16x16x32_bf16 v[36:39], v[166:169], v[198:201], 0
	v_mfma_f32_16x16x32_bf16 v[28:31], v[158:161], v[206:209], 0
	v_mfma_f32_16x16x32_bf16 v[20:23], v[166:169], v[206:209], 0
	v_mfma_f32_16x16x32_bf16 v[12:15], v[158:161], v[214:217], 0
	v_mfma_f32_16x16x32_bf16 v[4:7], v[166:169], v[214:217], 0
	v_mfma_f32_16x16x32_bf16 v[60:63], v[162:165], v[194:197], v[60:63]
	v_mfma_f32_16x16x32_bf16 v[52:55], v[170:173], v[194:197], v[52:55]
	v_mfma_f32_16x16x32_bf16 v[44:47], v[162:165], v[202:205], v[44:47]
	v_mfma_f32_16x16x32_bf16 v[36:39], v[170:173], v[202:205], v[36:39]
	v_mfma_f32_16x16x32_bf16 v[28:31], v[162:165], v[210:213], v[28:31]
	v_mfma_f32_16x16x32_bf16 v[20:23], v[170:173], v[210:213], v[20:23]
	v_mfma_f32_16x16x32_bf16 v[12:15], v[162:165], v[218:221], v[12:15]
	v_mfma_f32_16x16x32_bf16 v[4:7], v[170:173], v[218:221], v[4:7]
	v_mfma_f32_16x16x32_bf16 v[56:59], v[174:177], v[190:193], 0
	v_mfma_f32_16x16x32_bf16 v[48:51], v[182:185], v[190:193], 0
	v_mfma_f32_16x16x32_bf16 v[40:43], v[174:177], v[198:201], 0
	v_mfma_f32_16x16x32_bf16 v[32:35], v[182:185], v[198:201], 0
	v_mfma_f32_16x16x32_bf16 v[24:27], v[174:177], v[206:209], 0
	v_mfma_f32_16x16x32_bf16 v[16:19], v[182:185], v[206:209], 0
	v_mfma_f32_16x16x32_bf16 v[8:11], v[174:177], v[214:217], 0
	v_mfma_f32_16x16x32_bf16 v[0:3], v[182:185], v[214:217], 0
	v_mfma_f32_16x16x32_bf16 v[56:59], v[178:181], v[194:197], v[56:59]
	v_mfma_f32_16x16x32_bf16 v[48:51], v[186:189], v[194:197], v[48:51]
	v_mfma_f32_16x16x32_bf16 v[40:43], v[178:181], v[202:205], v[40:43]
	v_mfma_f32_16x16x32_bf16 v[32:35], v[186:189], v[202:205], v[32:35]
	v_mfma_f32_16x16x32_bf16 v[24:27], v[178:181], v[210:213], v[24:27]
	v_mfma_f32_16x16x32_bf16 v[16:19], v[186:189], v[210:213], v[16:19]
	v_mfma_f32_16x16x32_bf16 v[8:11], v[178:181], v[218:221], v[8:11]
	v_mfma_f32_16x16x32_bf16 v[0:3], v[186:189], v[218:221], v[0:3]
	s_setprio 0
	s_barrier
	s_add_i32 s72, 0, 0x18000
	s_add_i32 s73, 0, 0x1c000
	ds_read_b128 v[158:161], v254 offset:32768
	ds_read_b128 v[162:165], v254 offset:33792
	ds_read_b128 v[166:169], v254 offset:34816
	ds_read_b128 v[170:173], v254 offset:35840
	ds_read_b128 v[174:177], v254 offset:49152
	ds_read_b128 v[178:181], v254 offset:50176
	ds_read_b128 v[182:185], v254 offset:51200
	ds_read_b128 v[186:189], v254 offset:52224
	s_add_u32 s28, s54, 0x40000
	s_addc_u32 s29, s55, 0
	s_mov_b32 m0, s60
	ds_read_b128 v[190:193], v157 offset:32768
	ds_read_b128 v[194:197], v157 offset:33792
	ds_read_b128 v[198:201], v157 offset:34816
	ds_read_b128 v[202:205], v157 offset:35840
	ds_read_b128 v[206:209], v157 offset:36864
	ds_read_b128 v[210:213], v157 offset:37888
	ds_read_b128 v[214:217], v157 offset:38912
	ds_read_b128 v[218:221], v157 offset:39936
	global_load_lds_dwordx4 v132, s[28:29]
	s_mov_b32 m0, s61
	s_nop 0
	global_load_lds_dwordx4 v130, s[28:29]
	s_waitcnt vmcnt(8)
	s_waitcnt lgkmcnt(0)
	s_barrier
	s_setprio 1
	s_waitcnt lgkmcnt(0)
	v_mfma_f32_16x16x32_bf16 v[124:127], v[158:161], v[190:193], v[124:127]
	v_mfma_f32_16x16x32_bf16 v[116:119], v[166:169], v[190:193], v[116:119]
	v_mfma_f32_16x16x32_bf16 v[108:111], v[158:161], v[198:201], v[108:111]
	v_mfma_f32_16x16x32_bf16 v[100:103], v[166:169], v[198:201], v[100:103]
	v_mfma_f32_16x16x32_bf16 v[92:95], v[158:161], v[206:209], v[92:95]
	v_mfma_f32_16x16x32_bf16 v[84:87], v[166:169], v[206:209], v[84:87]
	v_mfma_f32_16x16x32_bf16 v[76:79], v[158:161], v[214:217], v[76:79]
	v_mfma_f32_16x16x32_bf16 v[68:71], v[166:169], v[214:217], v[68:71]
	v_mfma_f32_16x16x32_bf16 v[124:127], v[162:165], v[194:197], v[124:127]
	v_mfma_f32_16x16x32_bf16 v[116:119], v[170:173], v[194:197], v[116:119]
	v_mfma_f32_16x16x32_bf16 v[108:111], v[162:165], v[202:205], v[108:111]
	v_mfma_f32_16x16x32_bf16 v[100:103], v[170:173], v[202:205], v[100:103]
	v_mfma_f32_16x16x32_bf16 v[92:95], v[162:165], v[210:213], v[92:95]
	v_mfma_f32_16x16x32_bf16 v[84:87], v[170:173], v[210:213], v[84:87]
	v_mfma_f32_16x16x32_bf16 v[76:79], v[162:165], v[218:221], v[76:79]
	v_mfma_f32_16x16x32_bf16 v[68:71], v[170:173], v[218:221], v[68:71]
	v_mfma_f32_16x16x32_bf16 v[120:123], v[174:177], v[190:193], v[120:123]
	v_mfma_f32_16x16x32_bf16 v[112:115], v[182:185], v[190:193], v[112:115]
	v_mfma_f32_16x16x32_bf16 v[104:107], v[174:177], v[198:201], v[104:107]
	v_mfma_f32_16x16x32_bf16 v[96:99], v[182:185], v[198:201], v[96:99]
	v_mfma_f32_16x16x32_bf16 v[88:91], v[174:177], v[206:209], v[88:91]
	v_mfma_f32_16x16x32_bf16 v[80:83], v[182:185], v[206:209], v[80:83]
	v_mfma_f32_16x16x32_bf16 v[72:75], v[174:177], v[214:217], v[72:75]
	v_mfma_f32_16x16x32_bf16 v[64:67], v[182:185], v[214:217], v[64:67]
	v_mfma_f32_16x16x32_bf16 v[120:123], v[178:181], v[194:197], v[120:123]
	v_mfma_f32_16x16x32_bf16 v[112:115], v[186:189], v[194:197], v[112:115]
	v_mfma_f32_16x16x32_bf16 v[104:107], v[178:181], v[202:205], v[104:107]
	v_mfma_f32_16x16x32_bf16 v[96:99], v[186:189], v[202:205], v[96:99]
	v_mfma_f32_16x16x32_bf16 v[88:91], v[178:181], v[210:213], v[88:91]
	v_mfma_f32_16x16x32_bf16 v[80:83], v[186:189], v[210:213], v[80:83]
	v_mfma_f32_16x16x32_bf16 v[72:75], v[178:181], v[218:221], v[72:75]
	v_mfma_f32_16x16x32_bf16 v[64:67], v[186:189], v[218:221], v[64:67]
	s_setprio 0
	s_barrier
	s_add_i32 s28, s72, s57
	s_mov_b32 m0, s28
	ds_read_b128 v[190:193], v157 offset:49152
	ds_read_b128 v[194:197], v157 offset:50176
	ds_read_b128 v[198:201], v157 offset:51200
	ds_read_b128 v[202:205], v157 offset:52224
	ds_read_b128 v[206:209], v157 offset:53248
	ds_read_b128 v[210:213], v157 offset:54272
	ds_read_b128 v[214:217], v157 offset:55296
	ds_read_b128 v[218:221], v157 offset:56320
	global_load_lds_dwordx4 v142, s[98:99]
	s_add_i32 m0, s28, 0x2000
	s_add_u32 s28, s52, 0x40080
	s_addc_u32 s29, s53, 0
	s_add_i32 s52, s73, s57
	global_load_lds_dwordx4 v128, s[98:99]
	s_mov_b32 m0, s52
	s_nop 0
	global_load_lds_dwordx4 v142, s[28:29]
	s_add_i32 m0, s52, 0x2000
	s_nop 0
	global_load_lds_dwordx4 v128, s[28:29]
	s_mov_b32 m0, s62
	s_nop 0
	global_load_lds_dwordx4 v132, s[100:101]
	s_mov_b32 m0, s63
	s_nop 0
	global_load_lds_dwordx4 v130, s[100:101]
	s_waitcnt vmcnt(8)
	s_waitcnt lgkmcnt(0)
	s_barrier
	s_setprio 1
	s_waitcnt lgkmcnt(0)
	v_mfma_f32_16x16x32_bf16 v[60:63], v[158:161], v[190:193], v[60:63]
	v_mfma_f32_16x16x32_bf16 v[52:55], v[166:169], v[190:193], v[52:55]
	v_mfma_f32_16x16x32_bf16 v[44:47], v[158:161], v[198:201], v[44:47]
	v_mfma_f32_16x16x32_bf16 v[36:39], v[166:169], v[198:201], v[36:39]
	v_mfma_f32_16x16x32_bf16 v[28:31], v[158:161], v[206:209], v[28:31]
	v_mfma_f32_16x16x32_bf16 v[20:23], v[166:169], v[206:209], v[20:23]
	v_mfma_f32_16x16x32_bf16 v[12:15], v[158:161], v[214:217], v[12:15]
	v_mfma_f32_16x16x32_bf16 v[4:7], v[166:169], v[214:217], v[4:7]
	v_mfma_f32_16x16x32_bf16 v[60:63], v[162:165], v[194:197], v[60:63]
	v_mfma_f32_16x16x32_bf16 v[52:55], v[170:173], v[194:197], v[52:55]
	v_mfma_f32_16x16x32_bf16 v[44:47], v[162:165], v[202:205], v[44:47]
	v_mfma_f32_16x16x32_bf16 v[36:39], v[170:173], v[202:205], v[36:39]
	v_mfma_f32_16x16x32_bf16 v[28:31], v[162:165], v[210:213], v[28:31]
	v_mfma_f32_16x16x32_bf16 v[20:23], v[170:173], v[210:213], v[20:23]
	v_mfma_f32_16x16x32_bf16 v[12:15], v[162:165], v[218:221], v[12:15]
	v_mfma_f32_16x16x32_bf16 v[4:7], v[170:173], v[218:221], v[4:7]
	v_mfma_f32_16x16x32_bf16 v[56:59], v[174:177], v[190:193], v[56:59]
	v_mfma_f32_16x16x32_bf16 v[48:51], v[182:185], v[190:193], v[48:51]
	v_mfma_f32_16x16x32_bf16 v[40:43], v[174:177], v[198:201], v[40:43]
	v_mfma_f32_16x16x32_bf16 v[32:35], v[182:185], v[198:201], v[32:35]
	v_mfma_f32_16x16x32_bf16 v[24:27], v[174:177], v[206:209], v[24:27]
	v_mfma_f32_16x16x32_bf16 v[16:19], v[182:185], v[206:209], v[16:19]
	v_mfma_f32_16x16x32_bf16 v[8:11], v[174:177], v[214:217], v[8:11]
	v_mfma_f32_16x16x32_bf16 v[0:3], v[182:185], v[214:217], v[0:3]
	v_mfma_f32_16x16x32_bf16 v[56:59], v[178:181], v[194:197], v[56:59]
	v_mfma_f32_16x16x32_bf16 v[48:51], v[186:189], v[194:197], v[48:51]
	v_mfma_f32_16x16x32_bf16 v[40:43], v[178:181], v[202:205], v[40:43]
	v_mfma_f32_16x16x32_bf16 v[32:35], v[186:189], v[202:205], v[32:35]
	v_mfma_f32_16x16x32_bf16 v[24:27], v[178:181], v[210:213], v[24:27]
	v_mfma_f32_16x16x32_bf16 v[16:19], v[186:189], v[210:213], v[16:19]
	v_mfma_f32_16x16x32_bf16 v[8:11], v[178:181], v[218:221], v[8:11]
	v_mfma_f32_16x16x32_bf16 v[0:3], v[186:189], v[218:221], v[0:3]
	s_setprio 0
	s_barrier
	s_add_i32 s71, s71, 2
	s_add_u32 s50, s50, 0x100
	s_addc_u32 s51, s51, 0
	s_add_u32 s69, s69, 0x100
	s_addc_u32 s70, s70, 0
	s_cmp_gt_u32 s71, 13

.LBB0_275:
	s_add_u32 s36, s62, 0x100
	s_addc_u32 s37, s63, 0
	s_mov_b32 s59, -2
	s_add_u32 s40, s60, 0x100
	s_addc_u32 s41, s61, 0
	s_add_i32 s28, 0, 0x10000
	s_cmp_eq_u32 s59, 40
	s_cselect_b32 s65, s55, s41
	s_cselect_b32 s64, s54, s40
	s_cselect_b32 s63, s57, s37
	s_cselect_b32 s62, s56, s36
	s_add_i32 s79, 0, 0x14000
	ds_read_b128 v[108:111], v254
	ds_read_b128 v[130:133], v254 offset:1024
	ds_read_b128 v[134:137], v254 offset:2048
	ds_read_b128 v[180:183], v254 offset:3072
	ds_read_b128 v[184:187], v254 offset:16384
	ds_read_b128 v[188:191], v254 offset:17408
	ds_read_b128 v[192:195], v254 offset:18432
	ds_read_b128 v[196:199], v254 offset:19456
	s_add_i32 m0, s68, 0xc000
	ds_read_b128 v[200:203], v231
	ds_read_b128 v[204:207], v231 offset:1024
	ds_read_b128 v[208:211], v231 offset:2048
	ds_read_b128 v[212:215], v231 offset:3072
	ds_read_b128 v[216:219], v231 offset:4096
	ds_read_b128 v[232:235], v231 offset:5120
	ds_read_b128 v[236:239], v231 offset:6144
	ds_read_b128 v[240:243], v231 offset:7168
	global_load_lds_dwordx4 v176, s[60:61]
	s_add_i32 m0, s68, 0xe000
	s_nop 0
	global_load_lds_dwordx4 v178, s[60:61]
	s_waitcnt vmcnt(8)
	s_waitcnt lgkmcnt(0)
	s_barrier
	s_setprio 1
	s_waitcnt lgkmcnt(0)
	v_mfma_f32_16x16x32_bf16 v[138:141], v[108:111], v[200:203], 0
	v_mfma_f32_16x16x32_bf16 v[92:95], v[134:137], v[200:203], 0
	v_mfma_f32_16x16x32_bf16 v[126:129], v[108:111], v[208:211], 0
	v_mfma_f32_16x16x32_bf16 v[88:91], v[134:137], v[208:211], 0
	v_mfma_f32_16x16x32_bf16 v[122:125], v[108:111], v[216:219], 0
	v_mfma_f32_16x16x32_bf16 v[84:87], v[134:137], v[216:219], 0
	v_mfma_f32_16x16x32_bf16 v[118:121], v[108:111], v[236:239], 0
	v_mfma_f32_16x16x32_bf16 v[80:83], v[134:137], v[236:239], 0
	v_mfma_f32_16x16x32_bf16 v[138:141], v[130:133], v[204:207], v[138:141]
	v_mfma_f32_16x16x32_bf16 v[92:95], v[180:183], v[204:207], v[92:95]
	v_mfma_f32_16x16x32_bf16 v[126:129], v[130:133], v[212:215], v[126:129]
	v_mfma_f32_16x16x32_bf16 v[88:91], v[180:183], v[212:215], v[88:91]
	v_mfma_f32_16x16x32_bf16 v[122:125], v[130:133], v[232:235], v[122:125]
	v_mfma_f32_16x16x32_bf16 v[84:87], v[180:183], v[232:235], v[84:87]
	v_mfma_f32_16x16x32_bf16 v[118:121], v[130:133], v[240:243], v[118:121]
	v_mfma_f32_16x16x32_bf16 v[80:83], v[180:183], v[240:243], v[80:83]
	v_mfma_f32_16x16x32_bf16 v[60:63], v[184:187], v[200:203], 0
	v_mfma_f32_16x16x32_bf16 v[28:31], v[192:195], v[200:203], 0
	v_mfma_f32_16x16x32_bf16 v[56:59], v[184:187], v[208:211], 0
	v_mfma_f32_16x16x32_bf16 v[24:27], v[192:195], v[208:211], 0
	v_mfma_f32_16x16x32_bf16 v[52:55], v[184:187], v[216:219], 0
	v_mfma_f32_16x16x32_bf16 v[20:23], v[192:195], v[216:219], 0
	v_mfma_f32_16x16x32_bf16 v[48:51], v[184:187], v[236:239], 0
	v_mfma_f32_16x16x32_bf16 v[16:19], v[192:195], v[236:239], 0
	v_mfma_f32_16x16x32_bf16 v[60:63], v[188:191], v[204:207], v[60:63]
	v_mfma_f32_16x16x32_bf16 v[28:31], v[196:199], v[204:207], v[28:31]
	v_mfma_f32_16x16x32_bf16 v[56:59], v[188:191], v[212:215], v[56:59]
	v_mfma_f32_16x16x32_bf16 v[24:27], v[196:199], v[212:215], v[24:27]
	v_mfma_f32_16x16x32_bf16 v[52:55], v[188:191], v[232:235], v[52:55]
	v_mfma_f32_16x16x32_bf16 v[20:23], v[196:199], v[232:235], v[20:23]
	v_mfma_f32_16x16x32_bf16 v[48:51], v[188:191], v[240:243], v[48:51]
	v_mfma_f32_16x16x32_bf16 v[16:19], v[196:199], v[240:243], v[16:19]
	s_setprio 0
	s_barrier
	s_add_i32 s28, s28, s67
	s_mov_b32 m0, s28
	ds_read_b128 v[200:203], v231 offset:16384
	ds_read_b128 v[204:207], v231 offset:17408
	ds_read_b128 v[208:211], v231 offset:18432
	ds_read_b128 v[212:215], v231 offset:19456
	ds_read_b128 v[216:219], v231 offset:20480
	ds_read_b128 v[232:235], v231 offset:21504
	ds_read_b128 v[236:239], v231 offset:22528
	ds_read_b128 v[240:243], v231 offset:23552
	global_load_lds_dwordx4 v142, s[62:63]
	s_add_u32 s98, s62, 0x80
	s_addc_u32 s99, s63, 0
	s_add_i32 m0, s28, 0x2000
	s_add_u32 s28, s62, 0xb0000
	s_addc_u32 s29, s63, 0
	s_add_i32 s60, s79, s67
	global_load_lds_dwordx4 v156, s[62:63]
	s_mov_b32 m0, s60
	s_nop 0
	global_load_lds_dwordx4 v142, s[28:29]
	s_add_i32 m0, s60, 0x2000
	s_nop 0
	global_load_lds_dwordx4 v156, s[28:29]
	s_mov_b32 m0, s68
	s_nop 0
	global_load_lds_dwordx4 v142, s[64:65]
	s_add_u32 s100, s64, 0x80
	s_addc_u32 s101, s65, 0
	s_mov_b32 m0, s69
	s_nop 0
	global_load_lds_dwordx4 v156, s[64:65]
	s_waitcnt vmcnt(8)
	s_waitcnt lgkmcnt(0)
	s_barrier
	s_setprio 1
	s_waitcnt lgkmcnt(0)
	v_mfma_f32_16x16x32_bf16 v[112:115], v[108:111], v[200:203], 0
	v_mfma_f32_16x16x32_bf16 v[76:79], v[134:137], v[200:203], 0
	v_mfma_f32_16x16x32_bf16 v[104:107], v[108:111], v[208:211], 0
	v_mfma_f32_16x16x32_bf16 v[72:75], v[134:137], v[208:211], 0
	v_mfma_f32_16x16x32_bf16 v[100:103], v[108:111], v[216:219], 0
	v_mfma_f32_16x16x32_bf16 v[68:71], v[134:137], v[216:219], 0
	v_mfma_f32_16x16x32_bf16 v[96:99], v[108:111], v[236:239], 0
	v_mfma_f32_16x16x32_bf16 v[64:67], v[134:137], v[236:239], 0
	v_mfma_f32_16x16x32_bf16 v[112:115], v[130:133], v[204:207], v[112:115]
	v_mfma_f32_16x16x32_bf16 v[76:79], v[180:183], v[204:207], v[76:79]
	v_mfma_f32_16x16x32_bf16 v[104:107], v[130:133], v[212:215], v[104:107]
	v_mfma_f32_16x16x32_bf16 v[72:75], v[180:183], v[212:215], v[72:75]
	v_mfma_f32_16x16x32_bf16 v[100:103], v[130:133], v[232:235], v[100:103]
	v_mfma_f32_16x16x32_bf16 v[68:71], v[180:183], v[232:235], v[68:71]
	v_mfma_f32_16x16x32_bf16 v[96:99], v[130:133], v[240:243], v[96:99]
	v_mfma_f32_16x16x32_bf16 v[64:67], v[180:183], v[240:243], v[64:67]
	v_mfma_f32_16x16x32_bf16 v[44:47], v[184:187], v[200:203], 0
	v_mfma_f32_16x16x32_bf16 v[12:15], v[192:195], v[200:203], 0
	v_mfma_f32_16x16x32_bf16 v[40:43], v[184:187], v[208:211], 0
	v_mfma_f32_16x16x32_bf16 v[8:11], v[192:195], v[208:211], 0
	v_mfma_f32_16x16x32_bf16 v[36:39], v[184:187], v[216:219], 0
	v_mfma_f32_16x16x32_bf16 v[4:7], v[192:195], v[216:219], 0
	v_mfma_f32_16x16x32_bf16 v[32:35], v[184:187], v[236:239], 0
	v_mfma_f32_16x16x32_bf16 v[0:3], v[192:195], v[236:239], 0
	v_mfma_f32_16x16x32_bf16 v[44:47], v[188:191], v[204:207], v[44:47]
	v_mfma_f32_16x16x32_bf16 v[12:15], v[196:199], v[204:207], v[12:15]
	v_mfma_f32_16x16x32_bf16 v[40:43], v[188:191], v[212:215], v[40:43]
	v_mfma_f32_16x16x32_bf16 v[8:11], v[196:199], v[212:215], v[8:11]
	v_mfma_f32_16x16x32_bf16 v[36:39], v[188:191], v[232:235], v[36:39]
	v_mfma_f32_16x16x32_bf16 v[4:7], v[196:199], v[232:235], v[4:7]
	v_mfma_f32_16x16x32_bf16 v[32:35], v[188:191], v[240:243], v[32:35]
	v_mfma_f32_16x16x32_bf16 v[0:3], v[196:199], v[240:243], v[0:3]
	s_setprio 0
	s_barrier
	s_add_i32 s60, 0, 0x18000
	s_add_i32 s61, 0, 0x1c000
	ds_read_b128 v[108:111], v254 offset:32768
	ds_read_b128 v[130:133], v254 offset:33792
	ds_read_b128 v[134:137], v254 offset:34816
	ds_read_b128 v[180:183], v254 offset:35840
	ds_read_b128 v[184:187], v254 offset:49152
	ds_read_b128 v[188:191], v254 offset:50176
	ds_read_b128 v[192:195], v254 offset:51200
	ds_read_b128 v[196:199], v254 offset:52224
	s_add_u32 s28, s64, 0xb0000
	s_addc_u32 s29, s65, 0
	s_mov_b32 m0, s70
	ds_read_b128 v[200:203], v231 offset:32768
	ds_read_b128 v[204:207], v231 offset:33792
	ds_read_b128 v[208:211], v231 offset:34816
	ds_read_b128 v[212:215], v231 offset:35840
	ds_read_b128 v[216:219], v231 offset:36864
	ds_read_b128 v[232:235], v231 offset:37888
	ds_read_b128 v[236:239], v231 offset:38912
	ds_read_b128 v[240:243], v231 offset:39936
	global_load_lds_dwordx4 v142, s[28:29]
	s_mov_b32 m0, s71
	s_nop 0
	global_load_lds_dwordx4 v156, s[28:29]
	s_waitcnt vmcnt(8)
	s_waitcnt lgkmcnt(0)
	s_barrier
	s_setprio 1
	s_waitcnt lgkmcnt(0)
	v_mfma_f32_16x16x32_bf16 v[138:141], v[108:111], v[200:203], v[138:141]
	v_mfma_f32_16x16x32_bf16 v[92:95], v[134:137], v[200:203], v[92:95]
	v_mfma_f32_16x16x32_bf16 v[126:129], v[108:111], v[208:211], v[126:129]
	v_mfma_f32_16x16x32_bf16 v[88:91], v[134:137], v[208:211], v[88:91]
	v_mfma_f32_16x16x32_bf16 v[122:125], v[108:111], v[216:219], v[122:125]
	v_mfma_f32_16x16x32_bf16 v[84:87], v[134:137], v[216:219], v[84:87]
	v_mfma_f32_16x16x32_bf16 v[116:119], v[108:111], v[236:239], v[118:121]
	v_mfma_f32_16x16x32_bf16 v[80:83], v[134:137], v[236:239], v[80:83]
	v_mfma_f32_16x16x32_bf16 v[138:141], v[130:133], v[204:207], v[138:141]
	v_mfma_f32_16x16x32_bf16 v[92:95], v[180:183], v[204:207], v[92:95]
	v_mfma_f32_16x16x32_bf16 v[126:129], v[130:133], v[212:215], v[126:129]
	v_mfma_f32_16x16x32_bf16 v[88:91], v[180:183], v[212:215], v[88:91]
	v_mfma_f32_16x16x32_bf16 v[122:125], v[130:133], v[232:235], v[122:125]
	v_mfma_f32_16x16x32_bf16 v[84:87], v[180:183], v[232:235], v[84:87]
	v_mfma_f32_16x16x32_bf16 v[118:121], v[130:133], v[240:243], v[116:119]
	v_mfma_f32_16x16x32_bf16 v[80:83], v[180:183], v[240:243], v[80:83]
	v_mfma_f32_16x16x32_bf16 v[60:63], v[184:187], v[200:203], v[60:63]
	v_mfma_f32_16x16x32_bf16 v[28:31], v[192:195], v[200:203], v[28:31]
	v_mfma_f32_16x16x32_bf16 v[56:59], v[184:187], v[208:211], v[56:59]
	v_mfma_f32_16x16x32_bf16 v[24:27], v[192:195], v[208:211], v[24:27]
	v_mfma_f32_16x16x32_bf16 v[52:55], v[184:187], v[216:219], v[52:55]
	v_mfma_f32_16x16x32_bf16 v[20:23], v[192:195], v[216:219], v[20:23]
	v_mfma_f32_16x16x32_bf16 v[48:51], v[184:187], v[236:239], v[48:51]
	v_mfma_f32_16x16x32_bf16 v[16:19], v[192:195], v[236:239], v[16:19]
	v_mfma_f32_16x16x32_bf16 v[60:63], v[188:191], v[204:207], v[60:63]
	v_mfma_f32_16x16x32_bf16 v[28:31], v[196:199], v[204:207], v[28:31]
	v_mfma_f32_16x16x32_bf16 v[56:59], v[188:191], v[212:215], v[56:59]
	v_mfma_f32_16x16x32_bf16 v[24:27], v[196:199], v[212:215], v[24:27]
	v_mfma_f32_16x16x32_bf16 v[52:55], v[188:191], v[232:235], v[52:55]
	v_mfma_f32_16x16x32_bf16 v[20:23], v[196:199], v[232:235], v[20:23]
	v_mfma_f32_16x16x32_bf16 v[48:51], v[188:191], v[240:243], v[48:51]
	v_mfma_f32_16x16x32_bf16 v[16:19], v[196:199], v[240:243], v[16:19]
	s_setprio 0
	s_barrier
	s_add_i32 s28, s60, s67
	s_mov_b32 m0, s28
	ds_read_b128 v[200:203], v231 offset:49152
	ds_read_b128 v[204:207], v231 offset:50176
	ds_read_b128 v[208:211], v231 offset:51200
	ds_read_b128 v[212:215], v231 offset:52224
	ds_read_b128 v[216:219], v231 offset:53248
	ds_read_b128 v[232:235], v231 offset:54272
	ds_read_b128 v[236:239], v231 offset:55296
	ds_read_b128 v[240:243], v231 offset:56320
	global_load_lds_dwordx4 v142, s[98:99]
	s_add_i32 m0, s28, 0x2000
	s_add_u32 s28, s62, 0xb0080
	s_addc_u32 s29, s63, 0
	s_add_i32 s60, s61, s67
	global_load_lds_dwordx4 v156, s[98:99]
	s_mov_b32 m0, s60
	s_nop 0
	global_load_lds_dwordx4 v142, s[28:29]
	s_add_i32 m0, s60, 0x2000
	s_nop 0
	global_load_lds_dwordx4 v156, s[28:29]
	s_mov_b32 m0, s74
	s_nop 0
	global_load_lds_dwordx4 v142, s[100:101]
	s_mov_b32 m0, s75
	s_nop 0
	global_load_lds_dwordx4 v156, s[100:101]
	s_waitcnt vmcnt(8)
	s_waitcnt lgkmcnt(0)
	s_barrier
	s_setprio 1
	s_waitcnt lgkmcnt(0)
	v_mfma_f32_16x16x32_bf16 v[112:115], v[108:111], v[200:203], v[112:115]
	v_mfma_f32_16x16x32_bf16 v[76:79], v[134:137], v[200:203], v[76:79]
	v_mfma_f32_16x16x32_bf16 v[104:107], v[108:111], v[208:211], v[104:107]
	v_mfma_f32_16x16x32_bf16 v[72:75], v[134:137], v[208:211], v[72:75]
	v_mfma_f32_16x16x32_bf16 v[100:103], v[108:111], v[216:219], v[100:103]
	v_mfma_f32_16x16x32_bf16 v[68:71], v[134:137], v[216:219], v[68:71]
	v_mfma_f32_16x16x32_bf16 v[96:99], v[108:111], v[236:239], v[96:99]
	v_mfma_f32_16x16x32_bf16 v[64:67], v[134:137], v[236:239], v[64:67]
	v_mfma_f32_16x16x32_bf16 v[114:117], v[130:133], v[204:207], v[112:115]
	v_mfma_f32_16x16x32_bf16 v[76:79], v[180:183], v[204:207], v[76:79]
	v_mfma_f32_16x16x32_bf16 v[104:107], v[130:133], v[212:215], v[104:107]
	v_mfma_f32_16x16x32_bf16 v[72:75], v[180:183], v[212:215], v[72:75]
	v_mfma_f32_16x16x32_bf16 v[100:103], v[130:133], v[232:235], v[100:103]
	v_mfma_f32_16x16x32_bf16 v[68:71], v[180:183], v[232:235], v[68:71]
	v_mfma_f32_16x16x32_bf16 v[96:99], v[130:133], v[240:243], v[96:99]
	v_mfma_f32_16x16x32_bf16 v[64:67], v[180:183], v[240:243], v[64:67]
	v_mfma_f32_16x16x32_bf16 v[44:47], v[184:187], v[200:203], v[44:47]
	v_mfma_f32_16x16x32_bf16 v[12:15], v[192:195], v[200:203], v[12:15]
	v_mfma_f32_16x16x32_bf16 v[40:43], v[184:187], v[208:211], v[40:43]
	v_mfma_f32_16x16x32_bf16 v[8:11], v[192:195], v[208:211], v[8:11]
	v_mfma_f32_16x16x32_bf16 v[36:39], v[184:187], v[216:219], v[36:39]
	v_mfma_f32_16x16x32_bf16 v[4:7], v[192:195], v[216:219], v[4:7]
	v_mfma_f32_16x16x32_bf16 v[32:35], v[184:187], v[236:239], v[32:35]
	v_mfma_f32_16x16x32_bf16 v[0:3], v[192:195], v[236:239], v[0:3]
	v_mfma_f32_16x16x32_bf16 v[44:47], v[188:191], v[204:207], v[44:47]
	v_mfma_f32_16x16x32_bf16 v[12:15], v[196:199], v[204:207], v[12:15]
	v_mfma_f32_16x16x32_bf16 v[40:43], v[188:191], v[212:215], v[40:43]
	v_mfma_f32_16x16x32_bf16 v[8:11], v[196:199], v[212:215], v[8:11]
	v_mfma_f32_16x16x32_bf16 v[36:39], v[188:191], v[232:235], v[36:39]
	v_mfma_f32_16x16x32_bf16 v[4:7], v[196:199], v[232:235], v[4:7]
	v_mfma_f32_16x16x32_bf16 v[32:35], v[188:191], v[240:243], v[32:35]
	v_mfma_f32_16x16x32_bf16 v[0:3], v[196:199], v[240:243], v[0:3]
	s_setprio 0
	s_barrier
	s_add_i32 s59, s59, 2
	s_add_u32 s36, s36, 0x100
	s_addc_u32 s37, s37, 0
	s_cmp_gt_u32 s59, 41
	s_mov_b64 s[60:61], s[40:41]

.LBB0_501:
	s_ashr_i32 s49, s48, 31
	s_lshl_b64 s[28:29], s[48:49], 19
	s_add_u32 s50, s96, s28
	s_addc_u32 s51, s97, s29
	s_and_b64 s[28:29], s[38:39], exec
	s_cselect_b32 s37, s51, s41
	s_cselect_b32 s49, s50, s40
	s_ashr_i32 s47, s46, 31
	s_lshl_b64 s[28:29], s[46:47], 19
	v_readlane_b32 s4, v250, 4
	s_add_u32 s52, s4, s28
	v_readlane_b32 s4, v250, 5
	s_addc_u32 s53, s4, s29
	s_and_b64 s[28:29], s[38:39], exec
	s_cselect_b32 s47, s53, s55
	s_cselect_b32 s58, s52, s54
	s_add_u32 s40, s40, 0x40080
	s_addc_u32 s41, s41, 0
	s_add_u32 s59, s54, 0x100
	s_addc_u32 s60, s55, 0
	s_mov_b32 s61, -2
	s_waitcnt lgkmcnt(0)
	s_add_u32 s28, s40, 0xfffc0080
	s_addc_u32 s29, s41, -1
	s_add_i32 s69, 0, 0x10000
	s_cmp_eq_u32 s61, 12
	s_cselect_b32 s57, s37, s29
	s_cselect_b32 s56, s49, s28
	s_cselect_b32 s55, s47, s60
	s_cselect_b32 s54, s58, s59
	s_add_i32 s70, 0, 0x14000
	ds_read_b128 v[138:141], v254
	ds_read_b128 v[160:163], v254 offset:1024
	ds_read_b128 v[164:167], v254 offset:2048
	ds_read_b128 v[168:171], v254 offset:3072
	ds_read_b128 v[172:175], v254 offset:16384
	ds_read_b128 v[176:179], v254 offset:17408
	ds_read_b128 v[180:183], v254 offset:18432
	ds_read_b128 v[184:187], v254 offset:19456
	s_add_i32 m0, s62, 0xc000
	ds_read_b128 v[188:191], v159
	ds_read_b128 v[192:195], v159 offset:1024
	ds_read_b128 v[196:199], v159 offset:2048
	ds_read_b128 v[200:203], v159 offset:3072
	ds_read_b128 v[204:207], v159 offset:4096
	ds_read_b128 v[208:211], v159 offset:5120
	ds_read_b128 v[212:215], v159 offset:6144
	ds_read_b128 v[216:219], v159 offset:7168
	global_load_lds_dwordx4 v134, s[40:41]
	s_add_i32 m0, s62, 0xe000
	s_nop 0
	global_load_lds_dwordx4 v136, s[40:41]
	s_waitcnt vmcnt(8)
	s_waitcnt lgkmcnt(0)
	s_barrier
	s_setprio 1
	s_waitcnt lgkmcnt(0)
	v_mfma_f32_16x16x32_bf16 v[124:127], v[138:141], v[188:191], 0
	v_mfma_f32_16x16x32_bf16 v[120:123], v[164:167], v[188:191], 0
	v_mfma_f32_16x16x32_bf16 v[108:111], v[138:141], v[196:199], 0
	v_mfma_f32_16x16x32_bf16 v[104:107], v[164:167], v[196:199], 0
	v_mfma_f32_16x16x32_bf16 v[92:95], v[138:141], v[204:207], 0
	v_mfma_f32_16x16x32_bf16 v[88:91], v[164:167], v[204:207], 0
	v_mfma_f32_16x16x32_bf16 v[76:79], v[138:141], v[212:215], 0
	v_mfma_f32_16x16x32_bf16 v[72:75], v[164:167], v[212:215], 0
	v_mfma_f32_16x16x32_bf16 v[124:127], v[160:163], v[192:195], v[124:127]
	v_mfma_f32_16x16x32_bf16 v[120:123], v[168:171], v[192:195], v[120:123]
	v_mfma_f32_16x16x32_bf16 v[108:111], v[160:163], v[200:203], v[108:111]
	v_mfma_f32_16x16x32_bf16 v[104:107], v[168:171], v[200:203], v[104:107]
	v_mfma_f32_16x16x32_bf16 v[92:95], v[160:163], v[208:211], v[92:95]
	v_mfma_f32_16x16x32_bf16 v[88:91], v[168:171], v[208:211], v[88:91]
	v_mfma_f32_16x16x32_bf16 v[76:79], v[160:163], v[216:219], v[76:79]
	v_mfma_f32_16x16x32_bf16 v[72:75], v[168:171], v[216:219], v[72:75]
	v_mfma_f32_16x16x32_bf16 v[116:119], v[172:175], v[188:191], 0
	v_mfma_f32_16x16x32_bf16 v[112:115], v[180:183], v[188:191], 0
	v_mfma_f32_16x16x32_bf16 v[100:103], v[172:175], v[196:199], 0
	v_mfma_f32_16x16x32_bf16 v[96:99], v[180:183], v[196:199], 0
	v_mfma_f32_16x16x32_bf16 v[84:87], v[172:175], v[204:207], 0
	v_mfma_f32_16x16x32_bf16 v[80:83], v[180:183], v[204:207], 0
	v_mfma_f32_16x16x32_bf16 v[68:71], v[172:175], v[212:215], 0
	v_mfma_f32_16x16x32_bf16 v[64:67], v[180:183], v[212:215], 0
	v_mfma_f32_16x16x32_bf16 v[116:119], v[176:179], v[192:195], v[116:119]
	v_mfma_f32_16x16x32_bf16 v[112:115], v[184:187], v[192:195], v[112:115]
	v_mfma_f32_16x16x32_bf16 v[100:103], v[176:179], v[200:203], v[100:103]
	v_mfma_f32_16x16x32_bf16 v[96:99], v[184:187], v[200:203], v[96:99]
	v_mfma_f32_16x16x32_bf16 v[84:87], v[176:179], v[208:211], v[84:87]
	v_mfma_f32_16x16x32_bf16 v[80:83], v[184:187], v[208:211], v[80:83]
	v_mfma_f32_16x16x32_bf16 v[68:71], v[176:179], v[216:219], v[68:71]
	v_mfma_f32_16x16x32_bf16 v[64:67], v[184:187], v[216:219], v[64:67]
	s_setprio 0
	s_barrier
	s_add_i32 s28, s69, s20
	s_mov_b32 m0, s28
	ds_read_b128 v[188:191], v159 offset:16384
	ds_read_b128 v[192:195], v159 offset:17408
	ds_read_b128 v[196:199], v159 offset:18432
	ds_read_b128 v[200:203], v159 offset:19456
	ds_read_b128 v[204:207], v159 offset:20480
	ds_read_b128 v[208:211], v159 offset:21504
	ds_read_b128 v[212:215], v159 offset:22528
	ds_read_b128 v[216:219], v159 offset:23552
	global_load_lds_dwordx4 v142, s[54:55]
	s_add_u32 s98, s54, 0x80
	s_addc_u32 s99, s55, 0
	s_add_i32 m0, s28, 0x2000
	s_add_u32 s28, s54, 0x40000
	s_addc_u32 s29, s55, 0
	s_add_i32 s69, s70, s20
	global_load_lds_dwordx4 v128, s[54:55]
	s_mov_b32 m0, s69
	s_nop 0
	global_load_lds_dwordx4 v142, s[28:29]
	s_add_i32 m0, s69, 0x2000
	s_nop 0
	global_load_lds_dwordx4 v128, s[28:29]
	s_mov_b32 m0, s62
	s_nop 0
	global_load_lds_dwordx4 v132, s[56:57]
	s_add_u32 s100, s56, 0x80
	s_addc_u32 s101, s57, 0
	s_mov_b32 m0, s63
	s_nop 0
	global_load_lds_dwordx4 v130, s[56:57]
	s_waitcnt vmcnt(8)
	s_waitcnt lgkmcnt(0)
	s_barrier
	s_setprio 1
	s_waitcnt lgkmcnt(0)
	v_mfma_f32_16x16x32_bf16 v[60:63], v[138:141], v[188:191], 0
	v_mfma_f32_16x16x32_bf16 v[56:59], v[164:167], v[188:191], 0
	v_mfma_f32_16x16x32_bf16 v[44:47], v[138:141], v[196:199], 0
	v_mfma_f32_16x16x32_bf16 v[40:43], v[164:167], v[196:199], 0
	v_mfma_f32_16x16x32_bf16 v[28:31], v[138:141], v[204:207], 0
	v_mfma_f32_16x16x32_bf16 v[24:27], v[164:167], v[204:207], 0
	v_mfma_f32_16x16x32_bf16 v[12:15], v[138:141], v[212:215], 0
	v_mfma_f32_16x16x32_bf16 v[8:11], v[164:167], v[212:215], 0
	v_mfma_f32_16x16x32_bf16 v[60:63], v[160:163], v[192:195], v[60:63]
	v_mfma_f32_16x16x32_bf16 v[56:59], v[168:171], v[192:195], v[56:59]
	v_mfma_f32_16x16x32_bf16 v[44:47], v[160:163], v[200:203], v[44:47]
	v_mfma_f32_16x16x32_bf16 v[40:43], v[168:171], v[200:203], v[40:43]
	v_mfma_f32_16x16x32_bf16 v[28:31], v[160:163], v[208:211], v[28:31]
	v_mfma_f32_16x16x32_bf16 v[24:27], v[168:171], v[208:211], v[24:27]
	v_mfma_f32_16x16x32_bf16 v[12:15], v[160:163], v[216:219], v[12:15]
	v_mfma_f32_16x16x32_bf16 v[8:11], v[168:171], v[216:219], v[8:11]
	v_mfma_f32_16x16x32_bf16 v[52:55], v[172:175], v[188:191], 0
	v_mfma_f32_16x16x32_bf16 v[48:51], v[180:183], v[188:191], 0
	v_mfma_f32_16x16x32_bf16 v[36:39], v[172:175], v[196:199], 0
	v_mfma_f32_16x16x32_bf16 v[32:35], v[180:183], v[196:199], 0
	v_mfma_f32_16x16x32_bf16 v[20:23], v[172:175], v[204:207], 0
	v_mfma_f32_16x16x32_bf16 v[16:19], v[180:183], v[204:207], 0
	v_mfma_f32_16x16x32_bf16 v[4:7], v[172:175], v[212:215], 0
	v_mfma_f32_16x16x32_bf16 v[0:3], v[180:183], v[212:215], 0
	v_mfma_f32_16x16x32_bf16 v[52:55], v[176:179], v[192:195], v[52:55]
	v_mfma_f32_16x16x32_bf16 v[48:51], v[184:187], v[192:195], v[48:51]
	v_mfma_f32_16x16x32_bf16 v[36:39], v[176:179], v[200:203], v[36:39]
	v_mfma_f32_16x16x32_bf16 v[32:35], v[184:187], v[200:203], v[32:35]
	v_mfma_f32_16x16x32_bf16 v[20:23], v[176:179], v[208:211], v[20:23]
	v_mfma_f32_16x16x32_bf16 v[16:19], v[184:187], v[208:211], v[16:19]
	v_mfma_f32_16x16x32_bf16 v[4:7], v[176:179], v[216:219], v[4:7]
	v_mfma_f32_16x16x32_bf16 v[0:3], v[184:187], v[216:219], v[0:3]
	s_setprio 0
	s_barrier
	s_add_i32 s69, 0, 0x18000
	s_add_i32 s70, 0, 0x1c000
	ds_read_b128 v[138:141], v254 offset:32768
	ds_read_b128 v[160:163], v254 offset:33792
	ds_read_b128 v[164:167], v254 offset:34816
	ds_read_b128 v[168:171], v254 offset:35840
	ds_read_b128 v[172:175], v254 offset:49152
	ds_read_b128 v[176:179], v254 offset:50176
	ds_read_b128 v[180:183], v254 offset:51200
	ds_read_b128 v[184:187], v254 offset:52224
	s_add_u32 s28, s56, 0x40000
	s_addc_u32 s29, s57, 0
	s_mov_b32 m0, s64
	ds_read_b128 v[188:191], v159 offset:32768
	ds_read_b128 v[192:195], v159 offset:33792
	ds_read_b128 v[196:199], v159 offset:34816
	ds_read_b128 v[200:203], v159 offset:35840
	ds_read_b128 v[204:207], v159 offset:36864
	ds_read_b128 v[208:211], v159 offset:37888
	ds_read_b128 v[212:215], v159 offset:38912
	ds_read_b128 v[216:219], v159 offset:39936
	global_load_lds_dwordx4 v132, s[28:29]
	s_mov_b32 m0, s65
	s_nop 0
	global_load_lds_dwordx4 v130, s[28:29]
	s_waitcnt vmcnt(8)
	s_waitcnt lgkmcnt(0)
	s_barrier
	s_setprio 1
	s_waitcnt lgkmcnt(0)
	v_mfma_f32_16x16x32_bf16 v[124:127], v[138:141], v[188:191], v[124:127]
	v_mfma_f32_16x16x32_bf16 v[120:123], v[164:167], v[188:191], v[120:123]
	v_mfma_f32_16x16x32_bf16 v[108:111], v[138:141], v[196:199], v[108:111]
	v_mfma_f32_16x16x32_bf16 v[104:107], v[164:167], v[196:199], v[104:107]
	v_mfma_f32_16x16x32_bf16 v[92:95], v[138:141], v[204:207], v[92:95]
	v_mfma_f32_16x16x32_bf16 v[88:91], v[164:167], v[204:207], v[88:91]
	v_mfma_f32_16x16x32_bf16 v[76:79], v[138:141], v[212:215], v[76:79]
	v_mfma_f32_16x16x32_bf16 v[72:75], v[164:167], v[212:215], v[72:75]
	v_mfma_f32_16x16x32_bf16 v[124:127], v[160:163], v[192:195], v[124:127]
	v_mfma_f32_16x16x32_bf16 v[120:123], v[168:171], v[192:195], v[120:123]
	v_mfma_f32_16x16x32_bf16 v[108:111], v[160:163], v[200:203], v[108:111]
	v_mfma_f32_16x16x32_bf16 v[104:107], v[168:171], v[200:203], v[104:107]
	v_mfma_f32_16x16x32_bf16 v[92:95], v[160:163], v[208:211], v[92:95]
	v_mfma_f32_16x16x32_bf16 v[88:91], v[168:171], v[208:211], v[88:91]
	v_mfma_f32_16x16x32_bf16 v[76:79], v[160:163], v[216:219], v[76:79]
	v_mfma_f32_16x16x32_bf16 v[72:75], v[168:171], v[216:219], v[72:75]
	v_mfma_f32_16x16x32_bf16 v[116:119], v[172:175], v[188:191], v[116:119]
	v_mfma_f32_16x16x32_bf16 v[112:115], v[180:183], v[188:191], v[112:115]
	v_mfma_f32_16x16x32_bf16 v[100:103], v[172:175], v[196:199], v[100:103]
	v_mfma_f32_16x16x32_bf16 v[96:99], v[180:183], v[196:199], v[96:99]
	v_mfma_f32_16x16x32_bf16 v[84:87], v[172:175], v[204:207], v[84:87]
	v_mfma_f32_16x16x32_bf16 v[80:83], v[180:183], v[204:207], v[80:83]
	v_mfma_f32_16x16x32_bf16 v[68:71], v[172:175], v[212:215], v[68:71]
	v_mfma_f32_16x16x32_bf16 v[64:67], v[180:183], v[212:215], v[64:67]
	v_mfma_f32_16x16x32_bf16 v[116:119], v[176:179], v[192:195], v[116:119]
	v_mfma_f32_16x16x32_bf16 v[112:115], v[184:187], v[192:195], v[112:115]
	v_mfma_f32_16x16x32_bf16 v[100:103], v[176:179], v[200:203], v[100:103]
	v_mfma_f32_16x16x32_bf16 v[96:99], v[184:187], v[200:203], v[96:99]
	v_mfma_f32_16x16x32_bf16 v[84:87], v[176:179], v[208:211], v[84:87]
	v_mfma_f32_16x16x32_bf16 v[80:83], v[184:187], v[208:211], v[80:83]
	v_mfma_f32_16x16x32_bf16 v[68:71], v[176:179], v[216:219], v[68:71]
	v_mfma_f32_16x16x32_bf16 v[64:67], v[184:187], v[216:219], v[64:67]
	s_setprio 0
	s_barrier
	s_add_i32 s28, s69, s20
	s_mov_b32 m0, s28
	ds_read_b128 v[188:191], v159 offset:49152
	ds_read_b128 v[192:195], v159 offset:50176
	ds_read_b128 v[196:199], v159 offset:51200
	ds_read_b128 v[200:203], v159 offset:52224
	ds_read_b128 v[204:207], v159 offset:53248
	ds_read_b128 v[208:211], v159 offset:54272
	ds_read_b128 v[212:215], v159 offset:55296
	ds_read_b128 v[216:219], v159 offset:56320
	global_load_lds_dwordx4 v142, s[98:99]
	s_add_i32 m0, s28, 0x2000
	s_add_u32 s28, s54, 0x40080
	s_addc_u32 s29, s55, 0
	s_add_i32 s54, s70, s20
	global_load_lds_dwordx4 v128, s[98:99]
	s_mov_b32 m0, s54
	s_nop 0
	global_load_lds_dwordx4 v142, s[28:29]
	s_add_i32 m0, s54, 0x2000
	s_nop 0
	global_load_lds_dwordx4 v128, s[28:29]
	s_mov_b32 m0, s66
	s_nop 0
	global_load_lds_dwordx4 v132, s[100:101]
	s_mov_b32 m0, s67
	s_nop 0
	global_load_lds_dwordx4 v130, s[100:101]
	s_waitcnt vmcnt(8)
	s_waitcnt lgkmcnt(0)
	s_barrier
	s_setprio 1
	s_waitcnt lgkmcnt(0)
	v_mfma_f32_16x16x32_bf16 v[60:63], v[138:141], v[188:191], v[60:63]
	v_mfma_f32_16x16x32_bf16 v[56:59], v[164:167], v[188:191], v[56:59]
	v_mfma_f32_16x16x32_bf16 v[44:47], v[138:141], v[196:199], v[44:47]
	v_mfma_f32_16x16x32_bf16 v[40:43], v[164:167], v[196:199], v[40:43]
	v_mfma_f32_16x16x32_bf16 v[28:31], v[138:141], v[204:207], v[28:31]
	v_mfma_f32_16x16x32_bf16 v[24:27], v[164:167], v[204:207], v[24:27]
	v_mfma_f32_16x16x32_bf16 v[12:15], v[138:141], v[212:215], v[12:15]
	v_mfma_f32_16x16x32_bf16 v[8:11], v[164:167], v[212:215], v[8:11]
	v_mfma_f32_16x16x32_bf16 v[60:63], v[160:163], v[192:195], v[60:63]
	v_mfma_f32_16x16x32_bf16 v[56:59], v[168:171], v[192:195], v[56:59]
	v_mfma_f32_16x16x32_bf16 v[44:47], v[160:163], v[200:203], v[44:47]
	v_mfma_f32_16x16x32_bf16 v[40:43], v[168:171], v[200:203], v[40:43]
	v_mfma_f32_16x16x32_bf16 v[28:31], v[160:163], v[208:211], v[28:31]
	v_mfma_f32_16x16x32_bf16 v[24:27], v[168:171], v[208:211], v[24:27]
	v_mfma_f32_16x16x32_bf16 v[12:15], v[160:163], v[216:219], v[12:15]
	v_mfma_f32_16x16x32_bf16 v[8:11], v[168:171], v[216:219], v[8:11]
	v_mfma_f32_16x16x32_bf16 v[52:55], v[172:175], v[188:191], v[52:55]
	v_mfma_f32_16x16x32_bf16 v[48:51], v[180:183], v[188:191], v[48:51]
	v_mfma_f32_16x16x32_bf16 v[36:39], v[172:175], v[196:199], v[36:39]
	v_mfma_f32_16x16x32_bf16 v[32:35], v[180:183], v[196:199], v[32:35]
	v_mfma_f32_16x16x32_bf16 v[20:23], v[172:175], v[204:207], v[20:23]
	v_mfma_f32_16x16x32_bf16 v[16:19], v[180:183], v[204:207], v[16:19]
	v_mfma_f32_16x16x32_bf16 v[4:7], v[172:175], v[212:215], v[4:7]
	v_mfma_f32_16x16x32_bf16 v[0:3], v[180:183], v[212:215], v[0:3]
	v_mfma_f32_16x16x32_bf16 v[52:55], v[176:179], v[192:195], v[52:55]
	v_mfma_f32_16x16x32_bf16 v[48:51], v[184:187], v[192:195], v[48:51]
	v_mfma_f32_16x16x32_bf16 v[36:39], v[176:179], v[200:203], v[36:39]
	v_mfma_f32_16x16x32_bf16 v[32:35], v[184:187], v[200:203], v[32:35]
	v_mfma_f32_16x16x32_bf16 v[20:23], v[176:179], v[208:211], v[20:23]
	v_mfma_f32_16x16x32_bf16 v[16:19], v[184:187], v[208:211], v[16:19]
	v_mfma_f32_16x16x32_bf16 v[4:7], v[176:179], v[216:219], v[4:7]
	v_mfma_f32_16x16x32_bf16 v[0:3], v[184:187], v[216:219], v[0:3]
	s_setprio 0
	s_barrier
	s_add_i32 s61, s61, 2
	s_add_u32 s40, s40, 0x100
	s_addc_u32 s41, s41, 0
	s_add_u32 s59, s59, 0x100
	s_addc_u32 s60, s60, 0
	s_cmp_gt_u32 s61, 13

.LBB0_894:
	s_ashr_i32 s47, s46, 31
	s_lshl_b64 s[28:29], s[46:47], 19
	s_add_u32 s48, s96, s28
	s_addc_u32 s49, s97, s29
	s_and_b64 s[28:29], s[38:39], exec
	s_cselect_b32 s47, s49, s53
	s_cselect_b32 s64, s48, s52
	s_ashr_i32 s45, s44, 31
	s_lshl_b64 s[28:29], s[44:45], 19
	v_readlane_b32 s4, v251, 47
	s_add_u32 s50, s4, s28
	v_readlane_b32 s4, v251, 48
	s_addc_u32 s51, s4, s29
	s_and_b64 s[28:29], s[38:39], exec
	s_cselect_b32 s45, s51, s55
	s_cselect_b32 s65, s50, s54
	s_add_u32 s52, s52, 0x40080
	s_addc_u32 s53, s53, 0
	s_add_u32 s66, s54, 0x100
	s_addc_u32 s67, s55, 0
	s_mov_b32 s68, -2
	s_waitcnt lgkmcnt(0)
	s_add_u32 s28, s52, 0xfffc0080
	s_addc_u32 s29, s53, -1
	s_add_i32 s69, 0, 0x10000
	s_cmp_eq_u32 s68, 12
	s_cselect_b32 s57, s47, s29
	s_cselect_b32 s56, s64, s28
	s_cselect_b32 s55, s45, s67
	s_cselect_b32 s54, s65, s66
	s_add_i32 s70, 0, 0x14000
	ds_read_b128 v[156:159], v254
	ds_read_b128 v[160:163], v254 offset:1024
	ds_read_b128 v[172:175], v254 offset:2048
	ds_read_b128 v[176:179], v254 offset:3072
	ds_read_b128 v[180:183], v254 offset:16384
	ds_read_b128 v[184:187], v254 offset:17408
	ds_read_b128 v[188:191], v254 offset:18432
	ds_read_b128 v[192:195], v254 offset:19456
	s_add_i32 m0, s20, 0xc000
	ds_read_b128 v[196:199], v170
	ds_read_b128 v[200:203], v170 offset:1024
	ds_read_b128 v[204:207], v170 offset:2048
	ds_read_b128 v[208:211], v170 offset:3072
	ds_read_b128 v[212:215], v170 offset:4096
	ds_read_b128 v[216:219], v170 offset:5120
	ds_read_b128 v[230:233], v170 offset:6144
	ds_read_b128 v[234:237], v170 offset:7168
	global_load_lds_dwordx4 v136, s[52:53]
	s_add_i32 m0, s20, 0xe000
	s_nop 0
	global_load_lds_dwordx4 v138, s[52:53]
	s_waitcnt vmcnt(8)
	s_waitcnt lgkmcnt(0)
	s_barrier
	s_setprio 1
	s_waitcnt lgkmcnt(0)
	v_mfma_f32_16x16x32_bf16 v[124:127], v[156:159], v[196:199], 0
	v_mfma_f32_16x16x32_bf16 v[120:123], v[172:175], v[196:199], 0
	v_mfma_f32_16x16x32_bf16 v[108:111], v[156:159], v[204:207], 0
	v_mfma_f32_16x16x32_bf16 v[104:107], v[172:175], v[204:207], 0
	v_mfma_f32_16x16x32_bf16 v[92:95], v[156:159], v[212:215], 0
	v_mfma_f32_16x16x32_bf16 v[88:91], v[172:175], v[212:215], 0
	v_mfma_f32_16x16x32_bf16 v[76:79], v[156:159], v[230:233], 0
	v_mfma_f32_16x16x32_bf16 v[72:75], v[172:175], v[230:233], 0
	v_mfma_f32_16x16x32_bf16 v[124:127], v[160:163], v[200:203], v[124:127]
	v_mfma_f32_16x16x32_bf16 v[120:123], v[176:179], v[200:203], v[120:123]
	v_mfma_f32_16x16x32_bf16 v[108:111], v[160:163], v[208:211], v[108:111]
	v_mfma_f32_16x16x32_bf16 v[104:107], v[176:179], v[208:211], v[104:107]
	v_mfma_f32_16x16x32_bf16 v[92:95], v[160:163], v[216:219], v[92:95]
	v_mfma_f32_16x16x32_bf16 v[88:91], v[176:179], v[216:219], v[88:91]
	v_mfma_f32_16x16x32_bf16 v[76:79], v[160:163], v[234:237], v[76:79]
	v_mfma_f32_16x16x32_bf16 v[72:75], v[176:179], v[234:237], v[72:75]
	v_mfma_f32_16x16x32_bf16 v[116:119], v[180:183], v[196:199], 0
	v_mfma_f32_16x16x32_bf16 v[112:115], v[188:191], v[196:199], 0
	v_mfma_f32_16x16x32_bf16 v[100:103], v[180:183], v[204:207], 0
	v_mfma_f32_16x16x32_bf16 v[96:99], v[188:191], v[204:207], 0
	v_mfma_f32_16x16x32_bf16 v[84:87], v[180:183], v[212:215], 0
	v_mfma_f32_16x16x32_bf16 v[80:83], v[188:191], v[212:215], 0
	v_mfma_f32_16x16x32_bf16 v[68:71], v[180:183], v[230:233], 0
	v_mfma_f32_16x16x32_bf16 v[64:67], v[188:191], v[230:233], 0
	v_mfma_f32_16x16x32_bf16 v[116:119], v[184:187], v[200:203], v[116:119]
	v_mfma_f32_16x16x32_bf16 v[112:115], v[192:195], v[200:203], v[112:115]
	v_mfma_f32_16x16x32_bf16 v[100:103], v[184:187], v[208:211], v[100:103]
	v_mfma_f32_16x16x32_bf16 v[96:99], v[192:195], v[208:211], v[96:99]
	v_mfma_f32_16x16x32_bf16 v[84:87], v[184:187], v[216:219], v[84:87]
	v_mfma_f32_16x16x32_bf16 v[80:83], v[192:195], v[216:219], v[80:83]
	v_mfma_f32_16x16x32_bf16 v[68:71], v[184:187], v[234:237], v[68:71]
	v_mfma_f32_16x16x32_bf16 v[64:67], v[192:195], v[234:237], v[64:67]
	s_setprio 0
	s_barrier
	s_add_i32 s28, s69, s2
	s_mov_b32 m0, s28
	ds_read_b128 v[196:199], v170 offset:16384
	ds_read_b128 v[200:203], v170 offset:17408
	ds_read_b128 v[204:207], v170 offset:18432
	ds_read_b128 v[208:211], v170 offset:19456
	ds_read_b128 v[212:215], v170 offset:20480
	ds_read_b128 v[216:219], v170 offset:21504
	ds_read_b128 v[230:233], v170 offset:22528
	ds_read_b128 v[234:237], v170 offset:23552
	global_load_lds_dwordx4 v132, s[54:55]
	s_add_u32 s98, s54, 0x80
	s_addc_u32 s99, s55, 0
	s_add_i32 m0, s28, 0x2000
	s_add_u32 s28, s54, 0x40000
	s_addc_u32 s29, s55, 0
	s_add_i32 s69, s70, s2
	global_load_lds_dwordx4 v128, s[54:55]
	s_mov_b32 m0, s69
	s_nop 0
	global_load_lds_dwordx4 v132, s[28:29]
	s_add_i32 m0, s69, 0x2000
	s_nop 0
	global_load_lds_dwordx4 v128, s[28:29]
	s_mov_b32 m0, s20
	s_nop 0
	global_load_lds_dwordx4 v134, s[56:57]
	s_add_u32 s100, s56, 0x80
	s_addc_u32 s101, s57, 0
	s_mov_b32 m0, s36
	s_nop 0
	global_load_lds_dwordx4 v130, s[56:57]
	s_waitcnt vmcnt(8)
	s_waitcnt lgkmcnt(0)
	s_barrier
	s_setprio 1
	s_waitcnt lgkmcnt(0)
	v_mfma_f32_16x16x32_bf16 v[60:63], v[156:159], v[196:199], 0
	v_mfma_f32_16x16x32_bf16 v[56:59], v[172:175], v[196:199], 0
	v_mfma_f32_16x16x32_bf16 v[48:51], v[156:159], v[204:207], 0
	v_mfma_f32_16x16x32_bf16 v[40:43], v[172:175], v[204:207], 0
	v_mfma_f32_16x16x32_bf16 v[32:35], v[156:159], v[212:215], 0
	v_mfma_f32_16x16x32_bf16 v[24:27], v[172:175], v[212:215], 0
	v_mfma_f32_16x16x32_bf16 v[16:19], v[156:159], v[230:233], 0
	v_mfma_f32_16x16x32_bf16 v[8:11], v[172:175], v[230:233], 0
	v_mfma_f32_16x16x32_bf16 v[60:63], v[160:163], v[200:203], v[60:63]
	v_mfma_f32_16x16x32_bf16 v[56:59], v[176:179], v[200:203], v[56:59]
	v_mfma_f32_16x16x32_bf16 v[48:51], v[160:163], v[208:211], v[48:51]
	v_mfma_f32_16x16x32_bf16 v[40:43], v[176:179], v[208:211], v[40:43]
	v_mfma_f32_16x16x32_bf16 v[32:35], v[160:163], v[216:219], v[32:35]
	v_mfma_f32_16x16x32_bf16 v[24:27], v[176:179], v[216:219], v[24:27]
	v_mfma_f32_16x16x32_bf16 v[16:19], v[160:163], v[234:237], v[16:19]
	v_mfma_f32_16x16x32_bf16 v[8:11], v[176:179], v[234:237], v[8:11]
	v_mfma_f32_16x16x32_bf16 v[52:55], v[180:183], v[196:199], 0
	v_mfma_f32_16x16x32_bf16 v[44:47], v[188:191], v[196:199], 0
	v_mfma_f32_16x16x32_bf16 v[36:39], v[180:183], v[204:207], 0
	v_mfma_f32_16x16x32_bf16 v[28:31], v[188:191], v[204:207], 0
	v_mfma_f32_16x16x32_bf16 v[20:23], v[180:183], v[212:215], 0
	v_mfma_f32_16x16x32_bf16 v[12:15], v[188:191], v[212:215], 0
	v_mfma_f32_16x16x32_bf16 v[4:7], v[180:183], v[230:233], 0
	v_mfma_f32_16x16x32_bf16 v[0:3], v[188:191], v[230:233], 0
	v_mfma_f32_16x16x32_bf16 v[52:55], v[184:187], v[200:203], v[52:55]
	v_mfma_f32_16x16x32_bf16 v[44:47], v[192:195], v[200:203], v[44:47]
	v_mfma_f32_16x16x32_bf16 v[36:39], v[184:187], v[208:211], v[36:39]
	v_mfma_f32_16x16x32_bf16 v[28:31], v[192:195], v[208:211], v[28:31]
	v_mfma_f32_16x16x32_bf16 v[20:23], v[184:187], v[216:219], v[20:23]
	v_mfma_f32_16x16x32_bf16 v[12:15], v[192:195], v[216:219], v[12:15]
	v_mfma_f32_16x16x32_bf16 v[4:7], v[184:187], v[234:237], v[4:7]
	v_mfma_f32_16x16x32_bf16 v[0:3], v[192:195], v[234:237], v[0:3]
	s_setprio 0
	s_barrier
	s_add_i32 s69, 0, 0x18000
	s_add_i32 s70, 0, 0x1c000
	ds_read_b128 v[156:159], v254 offset:32768
	ds_read_b128 v[160:163], v254 offset:33792
	ds_read_b128 v[172:175], v254 offset:34816
	ds_read_b128 v[176:179], v254 offset:35840
	ds_read_b128 v[180:183], v254 offset:49152
	ds_read_b128 v[184:187], v254 offset:50176
	ds_read_b128 v[188:191], v254 offset:51200
	ds_read_b128 v[192:195], v254 offset:52224
	s_add_u32 s28, s56, 0x40000
	s_addc_u32 s29, s57, 0
	s_mov_b32 m0, s37
	ds_read_b128 v[196:199], v170 offset:32768
	ds_read_b128 v[200:203], v170 offset:33792
	ds_read_b128 v[204:207], v170 offset:34816
	ds_read_b128 v[208:211], v170 offset:35840
	ds_read_b128 v[212:215], v170 offset:36864
	ds_read_b128 v[216:219], v170 offset:37888
	ds_read_b128 v[230:233], v170 offset:38912
	ds_read_b128 v[234:237], v170 offset:39936
	global_load_lds_dwordx4 v134, s[28:29]
	s_mov_b32 m0, s58
	s_nop 0
	global_load_lds_dwordx4 v130, s[28:29]
	s_waitcnt vmcnt(8)
	s_waitcnt lgkmcnt(0)
	s_barrier
	s_setprio 1
	s_waitcnt lgkmcnt(0)
	v_mfma_f32_16x16x32_bf16 v[124:127], v[156:159], v[196:199], v[124:127]
	v_mfma_f32_16x16x32_bf16 v[120:123], v[172:175], v[196:199], v[120:123]
	v_mfma_f32_16x16x32_bf16 v[108:111], v[156:159], v[204:207], v[108:111]
	v_mfma_f32_16x16x32_bf16 v[104:107], v[172:175], v[204:207], v[104:107]
	v_mfma_f32_16x16x32_bf16 v[92:95], v[156:159], v[212:215], v[92:95]
	v_mfma_f32_16x16x32_bf16 v[88:91], v[172:175], v[212:215], v[88:91]
	v_mfma_f32_16x16x32_bf16 v[76:79], v[156:159], v[230:233], v[76:79]
	v_mfma_f32_16x16x32_bf16 v[72:75], v[172:175], v[230:233], v[72:75]
	v_mfma_f32_16x16x32_bf16 v[124:127], v[160:163], v[200:203], v[124:127]
	v_mfma_f32_16x16x32_bf16 v[120:123], v[176:179], v[200:203], v[120:123]
	v_mfma_f32_16x16x32_bf16 v[108:111], v[160:163], v[208:211], v[108:111]
	v_mfma_f32_16x16x32_bf16 v[104:107], v[176:179], v[208:211], v[104:107]
	v_mfma_f32_16x16x32_bf16 v[92:95], v[160:163], v[216:219], v[92:95]
	v_mfma_f32_16x16x32_bf16 v[88:91], v[176:179], v[216:219], v[88:91]
	v_mfma_f32_16x16x32_bf16 v[76:79], v[160:163], v[234:237], v[76:79]
	v_mfma_f32_16x16x32_bf16 v[72:75], v[176:179], v[234:237], v[72:75]
	v_mfma_f32_16x16x32_bf16 v[116:119], v[180:183], v[196:199], v[116:119]
	v_mfma_f32_16x16x32_bf16 v[112:115], v[188:191], v[196:199], v[112:115]
	v_mfma_f32_16x16x32_bf16 v[100:103], v[180:183], v[204:207], v[100:103]
	v_mfma_f32_16x16x32_bf16 v[96:99], v[188:191], v[204:207], v[96:99]
	v_mfma_f32_16x16x32_bf16 v[84:87], v[180:183], v[212:215], v[84:87]
	v_mfma_f32_16x16x32_bf16 v[80:83], v[188:191], v[212:215], v[80:83]
	v_mfma_f32_16x16x32_bf16 v[68:71], v[180:183], v[230:233], v[68:71]
	v_mfma_f32_16x16x32_bf16 v[64:67], v[188:191], v[230:233], v[64:67]
	v_mfma_f32_16x16x32_bf16 v[116:119], v[184:187], v[200:203], v[116:119]
	v_mfma_f32_16x16x32_bf16 v[112:115], v[192:195], v[200:203], v[112:115]
	v_mfma_f32_16x16x32_bf16 v[100:103], v[184:187], v[208:211], v[100:103]
	v_mfma_f32_16x16x32_bf16 v[96:99], v[192:195], v[208:211], v[96:99]
	v_mfma_f32_16x16x32_bf16 v[84:87], v[184:187], v[216:219], v[84:87]
	v_mfma_f32_16x16x32_bf16 v[80:83], v[192:195], v[216:219], v[80:83]
	v_mfma_f32_16x16x32_bf16 v[68:71], v[184:187], v[234:237], v[68:71]
	v_mfma_f32_16x16x32_bf16 v[64:67], v[192:195], v[234:237], v[64:67]
	s_setprio 0
	s_barrier
	s_add_i32 s28, s69, s2
	s_mov_b32 m0, s28
	ds_read_b128 v[196:199], v170 offset:49152
	ds_read_b128 v[200:203], v170 offset:50176
	ds_read_b128 v[204:207], v170 offset:51200
	ds_read_b128 v[208:211], v170 offset:52224
	ds_read_b128 v[212:215], v170 offset:53248
	ds_read_b128 v[216:219], v170 offset:54272
	ds_read_b128 v[230:233], v170 offset:55296
	ds_read_b128 v[234:237], v170 offset:56320
	global_load_lds_dwordx4 v132, s[98:99]
	s_add_i32 m0, s28, 0x2000
	s_add_u32 s28, s54, 0x40080
	s_addc_u32 s29, s55, 0
	s_add_i32 s54, s70, s2
	global_load_lds_dwordx4 v128, s[98:99]
	s_mov_b32 m0, s54
	s_nop 0
	global_load_lds_dwordx4 v132, s[28:29]
	s_add_i32 m0, s54, 0x2000
	s_nop 0
	global_load_lds_dwordx4 v128, s[28:29]
	s_mov_b32 m0, s59
	s_nop 0
	global_load_lds_dwordx4 v134, s[100:101]
	s_mov_b32 m0, s60
	s_nop 0
	global_load_lds_dwordx4 v130, s[100:101]
	s_waitcnt vmcnt(8)
	s_waitcnt lgkmcnt(0)
	s_barrier
	s_setprio 1
	s_waitcnt lgkmcnt(0)
	v_mfma_f32_16x16x32_bf16 v[60:63], v[156:159], v[196:199], v[60:63]
	v_mfma_f32_16x16x32_bf16 v[56:59], v[172:175], v[196:199], v[56:59]
	v_mfma_f32_16x16x32_bf16 v[48:51], v[156:159], v[204:207], v[48:51]
	v_mfma_f32_16x16x32_bf16 v[40:43], v[172:175], v[204:207], v[40:43]
	v_mfma_f32_16x16x32_bf16 v[32:35], v[156:159], v[212:215], v[32:35]
	v_mfma_f32_16x16x32_bf16 v[24:27], v[172:175], v[212:215], v[24:27]
	v_mfma_f32_16x16x32_bf16 v[16:19], v[156:159], v[230:233], v[16:19]
	v_mfma_f32_16x16x32_bf16 v[8:11], v[172:175], v[230:233], v[8:11]
	v_mfma_f32_16x16x32_bf16 v[60:63], v[160:163], v[200:203], v[60:63]
	v_mfma_f32_16x16x32_bf16 v[56:59], v[176:179], v[200:203], v[56:59]
	v_mfma_f32_16x16x32_bf16 v[48:51], v[160:163], v[208:211], v[48:51]
	v_mfma_f32_16x16x32_bf16 v[40:43], v[176:179], v[208:211], v[40:43]
	v_mfma_f32_16x16x32_bf16 v[32:35], v[160:163], v[216:219], v[32:35]
	v_mfma_f32_16x16x32_bf16 v[24:27], v[176:179], v[216:219], v[24:27]
	v_mfma_f32_16x16x32_bf16 v[16:19], v[160:163], v[234:237], v[16:19]
	v_mfma_f32_16x16x32_bf16 v[8:11], v[176:179], v[234:237], v[8:11]
	v_mfma_f32_16x16x32_bf16 v[52:55], v[180:183], v[196:199], v[52:55]
	v_mfma_f32_16x16x32_bf16 v[44:47], v[188:191], v[196:199], v[44:47]
	v_mfma_f32_16x16x32_bf16 v[36:39], v[180:183], v[204:207], v[36:39]
	v_mfma_f32_16x16x32_bf16 v[28:31], v[188:191], v[204:207], v[28:31]
	v_mfma_f32_16x16x32_bf16 v[20:23], v[180:183], v[212:215], v[20:23]
	v_mfma_f32_16x16x32_bf16 v[12:15], v[188:191], v[212:215], v[12:15]
	v_mfma_f32_16x16x32_bf16 v[4:7], v[180:183], v[230:233], v[4:7]
	v_mfma_f32_16x16x32_bf16 v[0:3], v[188:191], v[230:233], v[0:3]
	v_mfma_f32_16x16x32_bf16 v[52:55], v[184:187], v[200:203], v[52:55]
	v_mfma_f32_16x16x32_bf16 v[44:47], v[192:195], v[200:203], v[44:47]
	v_mfma_f32_16x16x32_bf16 v[36:39], v[184:187], v[208:211], v[36:39]
	v_mfma_f32_16x16x32_bf16 v[28:31], v[192:195], v[208:211], v[28:31]
	v_mfma_f32_16x16x32_bf16 v[20:23], v[184:187], v[216:219], v[20:23]
	v_mfma_f32_16x16x32_bf16 v[12:15], v[192:195], v[216:219], v[12:15]
	v_mfma_f32_16x16x32_bf16 v[4:7], v[184:187], v[234:237], v[4:7]
	v_mfma_f32_16x16x32_bf16 v[0:3], v[192:195], v[234:237], v[0:3]
	s_setprio 0
	s_barrier
	s_add_i32 s68, s68, 2
	s_add_u32 s52, s52, 0x100
	s_addc_u32 s53, s53, 0
	s_add_u32 s66, s66, 0x100
	s_addc_u32 s67, s67, 0
	s_cmp_gt_u32 s68, 13

.LBB0_1082:
	s_ashr_i32 s55, s54, 31
	s_lshl_b64 s[28:29], s[54:55], 19
	s_add_u32 s56, s42, s28
	s_addc_u32 s57, s43, s29
	s_and_b64 s[28:29], s[36:37], exec
	s_cselect_b32 s55, s57, s63
	s_cselect_b32 s61, s56, s62
	s_ashr_i32 s53, s52, 31
	s_lshl_b64 s[28:29], s[52:53], 19
	s_add_u32 s58, s40, s28
	s_addc_u32 s59, s41, s29
	s_and_b64 s[28:29], s[36:37], exec
	s_cselect_b32 s53, s59, s65
	s_cselect_b32 s76, s58, s64
	s_add_u32 s77, s64, 0x100
	s_addc_u32 s78, s65, 0
	s_mov_b32 s79, -2
	s_add_u32 s64, s62, 0x100
	s_addc_u32 s65, s63, 0
	s_add_i32 s28, 0, 0x10000
	s_cmp_eq_u32 s79, 12
	s_cselect_b32 s69, s55, s65
	s_cselect_b32 s68, s61, s64
	s_cselect_b32 s67, s53, s78
	s_cselect_b32 s66, s76, s77
	s_add_i32 s80, 0, 0x14000
	ds_read_b128 v[124:127], v254
	ds_read_b128 v[128:131], v254 offset:1024
	ds_read_b128 v[174:177], v254 offset:2048
	ds_read_b128 v[178:181], v254 offset:3072
	ds_read_b128 v[182:185], v254 offset:16384
	ds_read_b128 v[186:189], v254 offset:17408
	ds_read_b128 v[190:193], v254 offset:18432
	ds_read_b128 v[194:197], v254 offset:19456
	s_add_i32 m0, s20, 0xc000
	ds_read_b128 v[200:203], v199
	ds_read_b128 v[204:207], v199 offset:1024
	ds_read_b128 v[208:211], v199 offset:2048
	ds_read_b128 v[212:215], v199 offset:3072
	ds_read_b128 v[216:219], v199 offset:4096
	ds_read_b128 v[230:233], v199 offset:5120
	ds_read_b128 v[234:237], v199 offset:6144
	ds_read_b128 v[238:241], v199 offset:7168
	global_load_lds_dwordx4 v170, s[62:63]
	s_add_i32 m0, s20, 0xe000
	s_nop 0
	global_load_lds_dwordx4 v172, s[62:63]
	s_waitcnt vmcnt(8)
	s_waitcnt lgkmcnt(0)
	s_barrier
	s_setprio 1
	s_waitcnt lgkmcnt(0)
	v_mfma_f32_16x16x32_bf16 v[132:135], v[124:127], v[200:203], 0
	v_mfma_f32_16x16x32_bf16 v[96:99], v[174:177], v[200:203], 0
	v_mfma_f32_16x16x32_bf16 v[120:123], v[124:127], v[208:211], 0
	v_mfma_f32_16x16x32_bf16 v[88:91], v[174:177], v[208:211], 0
	v_mfma_f32_16x16x32_bf16 v[116:119], v[124:127], v[216:219], 0
	v_mfma_f32_16x16x32_bf16 v[84:87], v[174:177], v[216:219], 0
	v_mfma_f32_16x16x32_bf16 v[112:115], v[124:127], v[234:237], 0
	v_mfma_f32_16x16x32_bf16 v[80:83], v[174:177], v[234:237], 0
	v_mfma_f32_16x16x32_bf16 v[132:135], v[128:131], v[204:207], v[132:135]
	v_mfma_f32_16x16x32_bf16 v[96:99], v[178:181], v[204:207], v[96:99]
	v_mfma_f32_16x16x32_bf16 v[120:123], v[128:131], v[212:215], v[120:123]
	v_mfma_f32_16x16x32_bf16 v[88:91], v[178:181], v[212:215], v[88:91]
	v_mfma_f32_16x16x32_bf16 v[116:119], v[128:131], v[230:233], v[116:119]
	v_mfma_f32_16x16x32_bf16 v[84:87], v[178:181], v[230:233], v[84:87]
	v_mfma_f32_16x16x32_bf16 v[112:115], v[128:131], v[238:241], v[112:115]
	v_mfma_f32_16x16x32_bf16 v[80:83], v[178:181], v[238:241], v[80:83]
	v_mfma_f32_16x16x32_bf16 v[64:67], v[182:185], v[200:203], 0
	v_mfma_f32_16x16x32_bf16 v[32:35], v[190:193], v[200:203], 0
	v_mfma_f32_16x16x32_bf16 v[56:59], v[182:185], v[208:211], 0
	v_mfma_f32_16x16x32_bf16 v[24:27], v[190:193], v[208:211], 0
	v_mfma_f32_16x16x32_bf16 v[52:55], v[182:185], v[216:219], 0
	v_mfma_f32_16x16x32_bf16 v[20:23], v[190:193], v[216:219], 0
	v_mfma_f32_16x16x32_bf16 v[48:51], v[182:185], v[234:237], 0
	v_mfma_f32_16x16x32_bf16 v[16:19], v[190:193], v[234:237], 0
	v_mfma_f32_16x16x32_bf16 v[64:67], v[186:189], v[204:207], v[64:67]
	v_mfma_f32_16x16x32_bf16 v[32:35], v[194:197], v[204:207], v[32:35]
	v_mfma_f32_16x16x32_bf16 v[56:59], v[186:189], v[212:215], v[56:59]
	v_mfma_f32_16x16x32_bf16 v[24:27], v[194:197], v[212:215], v[24:27]
	v_mfma_f32_16x16x32_bf16 v[52:55], v[186:189], v[230:233], v[52:55]
	v_mfma_f32_16x16x32_bf16 v[20:23], v[194:197], v[230:233], v[20:23]
	v_mfma_f32_16x16x32_bf16 v[48:51], v[186:189], v[238:241], v[48:51]
	v_mfma_f32_16x16x32_bf16 v[16:19], v[194:197], v[238:241], v[16:19]
	s_setprio 0
	s_barrier
	s_add_i32 s28, s28, s2
	s_mov_b32 m0, s28
	ds_read_b128 v[200:203], v199 offset:16384
	ds_read_b128 v[204:207], v199 offset:17408
	ds_read_b128 v[208:211], v199 offset:18432
	ds_read_b128 v[212:215], v199 offset:19456
	ds_read_b128 v[216:219], v199 offset:20480
	ds_read_b128 v[230:233], v199 offset:21504
	ds_read_b128 v[234:237], v199 offset:22528
	ds_read_b128 v[238:241], v199 offset:23552
	global_load_lds_dwordx4 v142, s[66:67]
	s_add_u32 s98, s66, 0x80
	s_addc_u32 s99, s67, 0
	s_add_i32 m0, s28, 0x2000
	s_add_u32 s28, s66, 0x40000
	s_addc_u32 s29, s67, 0
	s_add_i32 s62, s80, s2
	global_load_lds_dwordx4 v136, s[66:67]
	s_mov_b32 m0, s62
	s_nop 0
	global_load_lds_dwordx4 v142, s[28:29]
	s_add_i32 m0, s62, 0x2000
	s_nop 0
	global_load_lds_dwordx4 v136, s[28:29]
	s_mov_b32 m0, s20
	s_nop 0
	global_load_lds_dwordx4 v142, s[68:69]
	s_add_u32 s100, s68, 0x80
	s_addc_u32 s101, s69, 0
	s_mov_b32 m0, s39
	s_nop 0
	global_load_lds_dwordx4 v136, s[68:69]
	s_waitcnt vmcnt(8)
	s_waitcnt lgkmcnt(0)
	s_barrier
	s_setprio 1
	s_waitcnt lgkmcnt(0)
	v_mfma_f32_16x16x32_bf16 v[108:111], v[124:127], v[200:203], 0
	v_mfma_f32_16x16x32_bf16 v[76:79], v[174:177], v[200:203], 0
	v_mfma_f32_16x16x32_bf16 v[104:107], v[124:127], v[208:211], 0
	v_mfma_f32_16x16x32_bf16 v[72:75], v[174:177], v[208:211], 0
	v_mfma_f32_16x16x32_bf16 v[100:103], v[124:127], v[216:219], 0
	v_mfma_f32_16x16x32_bf16 v[68:71], v[174:177], v[216:219], 0
	v_mfma_f32_16x16x32_bf16 v[92:95], v[124:127], v[234:237], 0
	v_mfma_f32_16x16x32_bf16 v[60:63], v[174:177], v[234:237], 0
	v_mfma_f32_16x16x32_bf16 v[108:111], v[128:131], v[204:207], v[108:111]
	v_mfma_f32_16x16x32_bf16 v[76:79], v[178:181], v[204:207], v[76:79]
	v_mfma_f32_16x16x32_bf16 v[104:107], v[128:131], v[212:215], v[104:107]
	v_mfma_f32_16x16x32_bf16 v[72:75], v[178:181], v[212:215], v[72:75]
	v_mfma_f32_16x16x32_bf16 v[100:103], v[128:131], v[230:233], v[100:103]
	v_mfma_f32_16x16x32_bf16 v[68:71], v[178:181], v[230:233], v[68:71]
	v_mfma_f32_16x16x32_bf16 v[92:95], v[128:131], v[238:241], v[92:95]
	v_mfma_f32_16x16x32_bf16 v[60:63], v[178:181], v[238:241], v[60:63]
	v_mfma_f32_16x16x32_bf16 v[44:47], v[182:185], v[200:203], 0
	v_mfma_f32_16x16x32_bf16 v[12:15], v[190:193], v[200:203], 0
	v_mfma_f32_16x16x32_bf16 v[40:43], v[182:185], v[208:211], 0
	v_mfma_f32_16x16x32_bf16 v[8:11], v[190:193], v[208:211], 0
	v_mfma_f32_16x16x32_bf16 v[36:39], v[182:185], v[216:219], 0
	v_mfma_f32_16x16x32_bf16 v[4:7], v[190:193], v[216:219], 0
	v_mfma_f32_16x16x32_bf16 v[28:31], v[182:185], v[234:237], 0
	v_mfma_f32_16x16x32_bf16 v[0:3], v[190:193], v[234:237], 0
	v_mfma_f32_16x16x32_bf16 v[44:47], v[186:189], v[204:207], v[44:47]
	v_mfma_f32_16x16x32_bf16 v[12:15], v[194:197], v[204:207], v[12:15]
	v_mfma_f32_16x16x32_bf16 v[40:43], v[186:189], v[212:215], v[40:43]
	v_mfma_f32_16x16x32_bf16 v[8:11], v[194:197], v[212:215], v[8:11]
	v_mfma_f32_16x16x32_bf16 v[36:39], v[186:189], v[230:233], v[36:39]
	v_mfma_f32_16x16x32_bf16 v[4:7], v[194:197], v[230:233], v[4:7]
	v_mfma_f32_16x16x32_bf16 v[28:31], v[186:189], v[238:241], v[28:31]
	v_mfma_f32_16x16x32_bf16 v[0:3], v[194:197], v[238:241], v[0:3]
	s_setprio 0
	s_barrier
	s_add_i32 s62, 0, 0x18000
	s_add_i32 s63, 0, 0x1c000
	ds_read_b128 v[124:127], v254 offset:32768
	ds_read_b128 v[128:131], v254 offset:33792
	ds_read_b128 v[174:177], v254 offset:34816
	ds_read_b128 v[178:181], v254 offset:35840
	ds_read_b128 v[182:185], v254 offset:49152
	ds_read_b128 v[186:189], v254 offset:50176
	ds_read_b128 v[190:193], v254 offset:51200
	ds_read_b128 v[194:197], v254 offset:52224
	s_add_u32 s28, s68, 0x40000
	s_addc_u32 s29, s69, 0
	s_mov_b32 m0, s70
	ds_read_b128 v[200:203], v199 offset:32768
	ds_read_b128 v[204:207], v199 offset:33792
	ds_read_b128 v[208:211], v199 offset:34816
	ds_read_b128 v[212:215], v199 offset:35840
	ds_read_b128 v[216:219], v199 offset:36864
	ds_read_b128 v[230:233], v199 offset:37888
	ds_read_b128 v[234:237], v199 offset:38912
	ds_read_b128 v[238:241], v199 offset:39936
	global_load_lds_dwordx4 v142, s[28:29]
	s_mov_b32 m0, s71
	s_nop 0
	global_load_lds_dwordx4 v136, s[28:29]
	s_waitcnt vmcnt(8)
	s_waitcnt lgkmcnt(0)
	s_barrier
	s_setprio 1
	s_waitcnt lgkmcnt(0)
	v_mfma_f32_16x16x32_bf16 v[132:135], v[124:127], v[200:203], v[132:135]
	v_mfma_f32_16x16x32_bf16 v[96:99], v[174:177], v[200:203], v[96:99]
	v_mfma_f32_16x16x32_bf16 v[120:123], v[124:127], v[208:211], v[120:123]
	v_mfma_f32_16x16x32_bf16 v[88:91], v[174:177], v[208:211], v[88:91]
	v_mfma_f32_16x16x32_bf16 v[116:119], v[124:127], v[216:219], v[116:119]
	v_mfma_f32_16x16x32_bf16 v[84:87], v[174:177], v[216:219], v[84:87]
	v_mfma_f32_16x16x32_bf16 v[112:115], v[124:127], v[234:237], v[112:115]
	v_mfma_f32_16x16x32_bf16 v[80:83], v[174:177], v[234:237], v[80:83]
	v_mfma_f32_16x16x32_bf16 v[132:135], v[128:131], v[204:207], v[132:135]
	v_mfma_f32_16x16x32_bf16 v[96:99], v[178:181], v[204:207], v[96:99]
	v_mfma_f32_16x16x32_bf16 v[120:123], v[128:131], v[212:215], v[120:123]
	v_mfma_f32_16x16x32_bf16 v[88:91], v[178:181], v[212:215], v[88:91]
	v_mfma_f32_16x16x32_bf16 v[116:119], v[128:131], v[230:233], v[116:119]
	v_mfma_f32_16x16x32_bf16 v[84:87], v[178:181], v[230:233], v[84:87]
	v_mfma_f32_16x16x32_bf16 v[112:115], v[128:131], v[238:241], v[112:115]
	v_mfma_f32_16x16x32_bf16 v[80:83], v[178:181], v[238:241], v[80:83]
	v_mfma_f32_16x16x32_bf16 v[64:67], v[182:185], v[200:203], v[64:67]
	v_mfma_f32_16x16x32_bf16 v[32:35], v[190:193], v[200:203], v[32:35]
	v_mfma_f32_16x16x32_bf16 v[56:59], v[182:185], v[208:211], v[56:59]
	v_mfma_f32_16x16x32_bf16 v[24:27], v[190:193], v[208:211], v[24:27]
	v_mfma_f32_16x16x32_bf16 v[52:55], v[182:185], v[216:219], v[52:55]
	v_mfma_f32_16x16x32_bf16 v[20:23], v[190:193], v[216:219], v[20:23]
	v_mfma_f32_16x16x32_bf16 v[48:51], v[182:185], v[234:237], v[48:51]
	v_mfma_f32_16x16x32_bf16 v[16:19], v[190:193], v[234:237], v[16:19]
	v_mfma_f32_16x16x32_bf16 v[64:67], v[186:189], v[204:207], v[64:67]
	v_mfma_f32_16x16x32_bf16 v[32:35], v[194:197], v[204:207], v[32:35]
	v_mfma_f32_16x16x32_bf16 v[56:59], v[186:189], v[212:215], v[56:59]
	v_mfma_f32_16x16x32_bf16 v[24:27], v[194:197], v[212:215], v[24:27]
	v_mfma_f32_16x16x32_bf16 v[52:55], v[186:189], v[230:233], v[52:55]
	v_mfma_f32_16x16x32_bf16 v[20:23], v[194:197], v[230:233], v[20:23]
	v_mfma_f32_16x16x32_bf16 v[48:51], v[186:189], v[238:241], v[48:51]
	v_mfma_f32_16x16x32_bf16 v[16:19], v[194:197], v[238:241], v[16:19]
	s_setprio 0
	s_barrier
	s_add_i32 s28, s62, s2
	s_mov_b32 m0, s28
	ds_read_b128 v[200:203], v199 offset:49152
	ds_read_b128 v[204:207], v199 offset:50176
	ds_read_b128 v[208:211], v199 offset:51200
	ds_read_b128 v[212:215], v199 offset:52224
	ds_read_b128 v[216:219], v199 offset:53248
	ds_read_b128 v[230:233], v199 offset:54272
	ds_read_b128 v[234:237], v199 offset:55296
	ds_read_b128 v[238:241], v199 offset:56320
	global_load_lds_dwordx4 v142, s[98:99]
	s_add_i32 m0, s28, 0x2000
	s_add_u32 s28, s66, 0x40080
	s_addc_u32 s29, s67, 0
	s_add_i32 s62, s63, s2
	global_load_lds_dwordx4 v136, s[98:99]
	s_mov_b32 m0, s62
	s_nop 0
	global_load_lds_dwordx4 v142, s[28:29]
	s_add_i32 m0, s62, 0x2000
	s_nop 0
	global_load_lds_dwordx4 v136, s[28:29]
	s_mov_b32 m0, s72
	s_nop 0
	global_load_lds_dwordx4 v142, s[100:101]
	s_mov_b32 m0, s73
	s_nop 0
	global_load_lds_dwordx4 v136, s[100:101]
	s_waitcnt vmcnt(8)
	s_waitcnt lgkmcnt(0)
	s_barrier
	s_setprio 1
	s_waitcnt lgkmcnt(0)
	v_mfma_f32_16x16x32_bf16 v[108:111], v[124:127], v[200:203], v[108:111]
	v_mfma_f32_16x16x32_bf16 v[76:79], v[174:177], v[200:203], v[76:79]
	v_mfma_f32_16x16x32_bf16 v[104:107], v[124:127], v[208:211], v[104:107]
	v_mfma_f32_16x16x32_bf16 v[72:75], v[174:177], v[208:211], v[72:75]
	v_mfma_f32_16x16x32_bf16 v[100:103], v[124:127], v[216:219], v[100:103]
	v_mfma_f32_16x16x32_bf16 v[68:71], v[174:177], v[216:219], v[68:71]
	v_mfma_f32_16x16x32_bf16 v[92:95], v[124:127], v[234:237], v[92:95]
	v_mfma_f32_16x16x32_bf16 v[60:63], v[174:177], v[234:237], v[60:63]
	v_mfma_f32_16x16x32_bf16 v[108:111], v[128:131], v[204:207], v[108:111]
	v_mfma_f32_16x16x32_bf16 v[76:79], v[178:181], v[204:207], v[76:79]
	v_mfma_f32_16x16x32_bf16 v[104:107], v[128:131], v[212:215], v[104:107]
	v_mfma_f32_16x16x32_bf16 v[72:75], v[178:181], v[212:215], v[72:75]
	v_mfma_f32_16x16x32_bf16 v[100:103], v[128:131], v[230:233], v[100:103]
	v_mfma_f32_16x16x32_bf16 v[68:71], v[178:181], v[230:233], v[68:71]
	v_mfma_f32_16x16x32_bf16 v[92:95], v[128:131], v[238:241], v[92:95]
	v_mfma_f32_16x16x32_bf16 v[60:63], v[178:181], v[238:241], v[60:63]
	v_mfma_f32_16x16x32_bf16 v[44:47], v[182:185], v[200:203], v[44:47]
	v_mfma_f32_16x16x32_bf16 v[12:15], v[190:193], v[200:203], v[12:15]
	v_mfma_f32_16x16x32_bf16 v[40:43], v[182:185], v[208:211], v[40:43]
	v_mfma_f32_16x16x32_bf16 v[8:11], v[190:193], v[208:211], v[8:11]
	v_mfma_f32_16x16x32_bf16 v[36:39], v[182:185], v[216:219], v[36:39]
	v_mfma_f32_16x16x32_bf16 v[4:7], v[190:193], v[216:219], v[4:7]
	v_mfma_f32_16x16x32_bf16 v[28:31], v[182:185], v[234:237], v[28:31]
	v_mfma_f32_16x16x32_bf16 v[0:3], v[190:193], v[234:237], v[0:3]
	v_mfma_f32_16x16x32_bf16 v[44:47], v[186:189], v[204:207], v[44:47]
	v_mfma_f32_16x16x32_bf16 v[12:15], v[194:197], v[204:207], v[12:15]
	v_mfma_f32_16x16x32_bf16 v[40:43], v[186:189], v[212:215], v[40:43]
	v_mfma_f32_16x16x32_bf16 v[8:11], v[194:197], v[212:215], v[8:11]
	v_mfma_f32_16x16x32_bf16 v[36:39], v[186:189], v[230:233], v[36:39]
	v_mfma_f32_16x16x32_bf16 v[4:7], v[194:197], v[230:233], v[4:7]
	v_mfma_f32_16x16x32_bf16 v[28:31], v[186:189], v[238:241], v[28:31]
	v_mfma_f32_16x16x32_bf16 v[0:3], v[194:197], v[238:241], v[0:3]
	s_setprio 0
	s_barrier
	s_add_i32 s79, s79, 2
	s_add_u32 s77, s77, 0x100
	s_addc_u32 s78, s78, 0
	s_cmp_gt_u32 s79, 13
	s_mov_b64 s[62:63], s[64:65]
